# K-loops: all 80 LDS-DMA tile loads on scalar-base addressing (K-step bases in s[100:101] or vcc); no 64-bit VALU adds left in the K-loops
# speedup vs baseline: 1.0157x; 1.0014x over previous
.LBB0_108:
	s_add_u32 s26, s50, 0xfff80080
	s_addc_u32 s27, s51, -1
	s_add_i32 s67, 0, 0x10000
	v_add_u32_e32 v134, s67, v180
	ds_read_b128 v[182:185], v134
	ds_read_b128 v[186:189], v134 offset:1024
	ds_read_b128 v[190:193], v134 offset:2048
	ds_read_b128 v[194:197], v134 offset:3072
	s_cmp_eq_u32 s66, 28
	s_cselect_b32 s53, s43, s27
	s_cselect_b32 s52, s62, s26
	s_cselect_b32 s27, s23, s65
	s_cselect_b32 s26, s63, s64
	s_add_i32 m0, s7, 0xc000
	ds_read_b128 v[198:201], v181
	ds_read_b128 v[202:205], v181 offset:1024
	ds_read_b128 v[206:209], v181 offset:2048
	ds_read_b128 v[210:213], v181 offset:3072
	ds_read_b128 v[214:217], v181 offset:4096
	ds_read_b128 v[218:221], v181 offset:5120
	ds_read_b128 v[222:225], v181 offset:6144
	ds_read_b128 v[226:229], v181 offset:7168
	global_load_lds_dwordx4 v162, s[50:51]
	s_add_i32 m0, s7, 0xe000
	s_nop 0
	global_load_lds_dwordx4 v164, s[50:51]
	s_waitcnt lgkmcnt(8)
	s_barrier
	s_waitcnt lgkmcnt(0)
	s_setprio 1
	s_waitcnt lgkmcnt(0)
	v_mfma_f32_16x16x32_bf16 v[126:129], v[182:185], v[198:201], v[126:129]
	v_mfma_f32_16x16x32_bf16 v[118:121], v[190:193], v[198:201], v[118:121]
	v_mfma_f32_16x16x32_bf16 v[110:113], v[182:185], v[206:209], v[110:113]
	v_mfma_f32_16x16x32_bf16 v[102:105], v[190:193], v[206:209], v[102:105]
	v_mfma_f32_16x16x32_bf16 v[94:97], v[182:185], v[214:217], v[94:97]
	v_mfma_f32_16x16x32_bf16 v[86:89], v[190:193], v[214:217], v[86:89]
	v_mfma_f32_16x16x32_bf16 v[78:81], v[182:185], v[222:225], v[78:81]
	v_mfma_f32_16x16x32_bf16 v[70:73], v[190:193], v[222:225], v[70:73]
	v_mfma_f32_16x16x32_bf16 v[126:129], v[186:189], v[202:205], v[126:129]
	v_mfma_f32_16x16x32_bf16 v[118:121], v[194:197], v[202:205], v[118:121]
	v_mfma_f32_16x16x32_bf16 v[110:113], v[186:189], v[210:213], v[110:113]
	v_mfma_f32_16x16x32_bf16 v[102:105], v[194:197], v[210:213], v[102:105]
	v_mfma_f32_16x16x32_bf16 v[94:97], v[186:189], v[218:221], v[94:97]
	v_mfma_f32_16x16x32_bf16 v[86:89], v[194:197], v[218:221], v[86:89]
	v_mfma_f32_16x16x32_bf16 v[78:81], v[186:189], v[226:229], v[78:81]
	v_mfma_f32_16x16x32_bf16 v[70:73], v[194:197], v[226:229], v[70:73]
	s_setprio 0
	s_barrier
	s_add_i32 s70, 0, 0x14000
	s_add_i32 s67, s67, s6
	v_add_u32_e32 v134, s70, v180
	s_mov_b32 m0, s67
	ds_read_b128 v[230:233], v134
	ds_read_b128 v[234:237], v134 offset:1024
	ds_read_b128 v[238:241], v134 offset:2048
	ds_read_b128 v[242:245], v134 offset:3072
	global_load_lds_dwordx4 v0, s[26:27]
	s_add_i32 m0, s67, 0x2000
	s_nop 0
	global_load_lds_dwordx4 v138, s[26:27]
	s_barrier
	s_waitcnt lgkmcnt(0)
	s_setprio 1
	s_waitcnt lgkmcnt(0)
	v_mfma_f32_16x16x32_bf16 v[122:125], v[230:233], v[198:201], v[122:125]
	v_mfma_f32_16x16x32_bf16 v[114:117], v[238:241], v[198:201], v[114:117]
	v_mfma_f32_16x16x32_bf16 v[106:109], v[230:233], v[206:209], v[106:109]
	v_mfma_f32_16x16x32_bf16 v[98:101], v[238:241], v[206:209], v[98:101]
	v_mfma_f32_16x16x32_bf16 v[90:93], v[230:233], v[214:217], v[90:93]
	v_mfma_f32_16x16x32_bf16 v[82:85], v[238:241], v[214:217], v[82:85]
	v_mfma_f32_16x16x32_bf16 v[74:77], v[230:233], v[222:225], v[74:77]
	v_mfma_f32_16x16x32_bf16 v[66:69], v[238:241], v[222:225], v[66:69]
	v_mfma_f32_16x16x32_bf16 v[122:125], v[234:237], v[202:205], v[122:125]
	v_mfma_f32_16x16x32_bf16 v[114:117], v[242:245], v[202:205], v[114:117]
	v_mfma_f32_16x16x32_bf16 v[106:109], v[234:237], v[210:213], v[106:109]
	v_mfma_f32_16x16x32_bf16 v[98:101], v[242:245], v[210:213], v[98:101]
	v_mfma_f32_16x16x32_bf16 v[90:93], v[234:237], v[218:221], v[90:93]
	v_mfma_f32_16x16x32_bf16 v[82:85], v[242:245], v[218:221], v[82:85]
	v_mfma_f32_16x16x32_bf16 v[74:77], v[234:237], v[226:229], v[74:77]
	v_mfma_f32_16x16x32_bf16 v[66:69], v[242:245], v[226:229], v[66:69]
	s_setprio 0
	s_mov_b32 m0, s7
	s_add_u32 vcc_lo, s52, s10
	s_addc_u32 vcc_hi, s53, s11
	s_barrier
	ds_read_b128 v[198:201], v181 offset:16384
	ds_read_b128 v[202:205], v181 offset:17408
	ds_read_b128 v[206:209], v181 offset:18432
	ds_read_b128 v[210:213], v181 offset:19456
	ds_read_b128 v[214:217], v181 offset:20480
	ds_read_b128 v[218:221], v181 offset:21504
	ds_read_b128 v[222:225], v181 offset:22528
	ds_read_b128 v[226:229], v181 offset:23552
	global_load_lds_dwordx4 v142, s[52:53]
	s_mov_b32 m0, s14
	s_nop 0
	global_load_lds_dwordx4 v140, s[52:53]
	s_barrier
	s_waitcnt lgkmcnt(0)
	s_setprio 1
	s_waitcnt lgkmcnt(0)
	v_mfma_f32_16x16x32_bf16 v[62:65], v[182:185], v[198:201], v[62:65]
	v_mfma_f32_16x16x32_bf16 v[54:57], v[190:193], v[198:201], v[54:57]
	v_mfma_f32_16x16x32_bf16 v[46:49], v[182:185], v[206:209], v[46:49]
	v_mfma_f32_16x16x32_bf16 v[38:41], v[190:193], v[206:209], v[38:41]
	v_mfma_f32_16x16x32_bf16 v[30:33], v[182:185], v[214:217], v[30:33]
	v_mfma_f32_16x16x32_bf16 v[22:25], v[190:193], v[214:217], v[22:25]
	v_mfma_f32_16x16x32_bf16 v[14:17], v[182:185], v[222:225], v[14:17]
	v_mfma_f32_16x16x32_bf16 v[6:9], v[190:193], v[222:225], v[6:9]
	v_mfma_f32_16x16x32_bf16 v[62:65], v[186:189], v[202:205], v[62:65]
	v_mfma_f32_16x16x32_bf16 v[54:57], v[194:197], v[202:205], v[54:57]
	v_mfma_f32_16x16x32_bf16 v[46:49], v[186:189], v[210:213], v[46:49]
	v_mfma_f32_16x16x32_bf16 v[38:41], v[194:197], v[210:213], v[38:41]
	v_mfma_f32_16x16x32_bf16 v[30:33], v[186:189], v[218:221], v[30:33]
	v_mfma_f32_16x16x32_bf16 v[22:25], v[194:197], v[218:221], v[22:25]
	v_mfma_f32_16x16x32_bf16 v[14:17], v[186:189], v[226:229], v[14:17]
	v_mfma_f32_16x16x32_bf16 v[6:9], v[194:197], v[226:229], v[6:9]
	s_setprio 0
	s_barrier
	s_add_u32 s68, s26, 0x80000
	s_addc_u32 s69, s27, 0
	s_add_i32 s67, s70, s6
	s_mov_b32 m0, s67
	s_nop 0
	global_load_lds_dwordx4 v0, s[68:69]
	s_add_i32 m0, s67, 0x2000
	s_nop 0
	global_load_lds_dwordx4 v138, s[68:69]
	s_waitcnt vmcnt(6)
	s_barrier
	s_setprio 1
	v_mfma_f32_16x16x32_bf16 v[58:61], v[230:233], v[198:201], v[58:61]
	v_mfma_f32_16x16x32_bf16 v[50:53], v[238:241], v[198:201], v[50:53]
	v_mfma_f32_16x16x32_bf16 v[42:45], v[230:233], v[206:209], v[42:45]
	v_mfma_f32_16x16x32_bf16 v[34:37], v[238:241], v[206:209], v[34:37]
	v_mfma_f32_16x16x32_bf16 v[26:29], v[230:233], v[214:217], v[26:29]
	v_mfma_f32_16x16x32_bf16 v[18:21], v[238:241], v[214:217], v[18:21]
	v_mfma_f32_16x16x32_bf16 v[10:13], v[230:233], v[222:225], v[10:13]
	v_mfma_f32_16x16x32_bf16 v[2:5], v[238:241], v[222:225], v[2:5]
	v_mfma_f32_16x16x32_bf16 v[58:61], v[234:237], v[202:205], v[58:61]
	v_mfma_f32_16x16x32_bf16 v[50:53], v[242:245], v[202:205], v[50:53]
	v_mfma_f32_16x16x32_bf16 v[42:45], v[234:237], v[210:213], v[42:45]
	v_mfma_f32_16x16x32_bf16 v[34:37], v[242:245], v[210:213], v[34:37]
	v_mfma_f32_16x16x32_bf16 v[26:29], v[234:237], v[218:221], v[26:29]
	v_mfma_f32_16x16x32_bf16 v[18:21], v[242:245], v[218:221], v[18:21]
	v_mfma_f32_16x16x32_bf16 v[10:13], v[234:237], v[226:229], v[10:13]
	v_mfma_f32_16x16x32_bf16 v[2:5], v[242:245], v[226:229], v[2:5]
	s_setprio 0
	s_add_i32 s67, 0, 0x18000
	v_add_u32_e32 v194, s67, v180
	s_barrier
	ds_read_b128 v[182:185], v194
	ds_read_b128 v[186:189], v194 offset:1024
	ds_read_b128 v[190:193], v194 offset:2048
	ds_read_b128 v[194:197], v194 offset:3072
	s_add_u32 s52, s52, 0x80000
	s_addc_u32 s53, s53, 0
	s_mov_b32 m0, s54
	ds_read_b128 v[198:201], v181 offset:32768
	ds_read_b128 v[202:205], v181 offset:33792
	ds_read_b128 v[206:209], v181 offset:34816
	ds_read_b128 v[210:213], v181 offset:35840
	ds_read_b128 v[214:217], v181 offset:36864
	ds_read_b128 v[218:221], v181 offset:37888
	ds_read_b128 v[222:225], v181 offset:38912
	ds_read_b128 v[226:229], v181 offset:39936
	global_load_lds_dwordx4 v142, s[52:53]
	s_mov_b32 m0, s55
	s_nop 0
	global_load_lds_dwordx4 v140, s[52:53]
	s_waitcnt lgkmcnt(8)
	s_barrier
	s_waitcnt lgkmcnt(0)
	s_setprio 1
	s_waitcnt lgkmcnt(0)
	v_mfma_f32_16x16x32_bf16 v[126:129], v[182:185], v[198:201], v[126:129]
	v_mfma_f32_16x16x32_bf16 v[118:121], v[190:193], v[198:201], v[118:121]
	v_mfma_f32_16x16x32_bf16 v[110:113], v[182:185], v[206:209], v[110:113]
	v_mfma_f32_16x16x32_bf16 v[102:105], v[190:193], v[206:209], v[102:105]
	v_mfma_f32_16x16x32_bf16 v[94:97], v[182:185], v[214:217], v[94:97]
	v_mfma_f32_16x16x32_bf16 v[86:89], v[190:193], v[214:217], v[86:89]
	v_mfma_f32_16x16x32_bf16 v[78:81], v[182:185], v[222:225], v[78:81]
	v_mfma_f32_16x16x32_bf16 v[70:73], v[190:193], v[222:225], v[70:73]
	v_mfma_f32_16x16x32_bf16 v[126:129], v[186:189], v[202:205], v[126:129]
	v_mfma_f32_16x16x32_bf16 v[118:121], v[194:197], v[202:205], v[118:121]
	v_mfma_f32_16x16x32_bf16 v[110:113], v[186:189], v[210:213], v[110:113]
	v_mfma_f32_16x16x32_bf16 v[102:105], v[194:197], v[210:213], v[102:105]
	v_mfma_f32_16x16x32_bf16 v[94:97], v[186:189], v[218:221], v[94:97]
	v_mfma_f32_16x16x32_bf16 v[86:89], v[194:197], v[218:221], v[86:89]
	v_mfma_f32_16x16x32_bf16 v[78:81], v[186:189], v[226:229], v[78:81]
	v_mfma_f32_16x16x32_bf16 v[70:73], v[194:197], v[226:229], v[70:73]
	s_setprio 0
	s_barrier
	s_add_i32 s52, 0, 0x1c000
	s_add_i32 s53, s67, s6
	v_add_u32_e32 v242, s52, v180
	s_add_u32 s100, s26, s10
	s_addc_u32 s101, s27, s11
	s_mov_b32 m0, s53
	ds_read_b128 v[230:233], v242
	ds_read_b128 v[234:237], v242 offset:1024
	ds_read_b128 v[238:241], v242 offset:2048
	ds_read_b128 v[242:245], v242 offset:3072
	global_load_lds_dwordx4 v0, s[100:101]
	s_add_u32 s100, s26, s10
	s_addc_u32 s101, s27, s11
	s_add_i32 m0, s53, 0x2000
	s_nop 0
	global_load_lds_dwordx4 v138, s[100:101]
	s_barrier
	s_waitcnt lgkmcnt(0)
	s_setprio 1
	s_waitcnt lgkmcnt(0)
	v_mfma_f32_16x16x32_bf16 v[122:125], v[230:233], v[198:201], v[122:125]
	v_mfma_f32_16x16x32_bf16 v[114:117], v[238:241], v[198:201], v[114:117]
	v_mfma_f32_16x16x32_bf16 v[106:109], v[230:233], v[206:209], v[106:109]
	v_mfma_f32_16x16x32_bf16 v[98:101], v[238:241], v[206:209], v[98:101]
	v_mfma_f32_16x16x32_bf16 v[90:93], v[230:233], v[214:217], v[90:93]
	v_mfma_f32_16x16x32_bf16 v[82:85], v[238:241], v[214:217], v[82:85]
	v_mfma_f32_16x16x32_bf16 v[74:77], v[230:233], v[222:225], v[74:77]
	v_mfma_f32_16x16x32_bf16 v[66:69], v[238:241], v[222:225], v[66:69]
	v_mfma_f32_16x16x32_bf16 v[122:125], v[234:237], v[202:205], v[122:125]
	v_mfma_f32_16x16x32_bf16 v[114:117], v[242:245], v[202:205], v[114:117]
	v_mfma_f32_16x16x32_bf16 v[106:109], v[234:237], v[210:213], v[106:109]
	v_mfma_f32_16x16x32_bf16 v[98:101], v[242:245], v[210:213], v[98:101]
	v_mfma_f32_16x16x32_bf16 v[90:93], v[234:237], v[218:221], v[90:93]
	v_mfma_f32_16x16x32_bf16 v[82:85], v[242:245], v[218:221], v[82:85]
	v_mfma_f32_16x16x32_bf16 v[74:77], v[234:237], v[226:229], v[74:77]
	v_mfma_f32_16x16x32_bf16 v[66:69], v[242:245], v[226:229], v[66:69]
	s_setprio 0
	s_mov_b32 m0, s57
	s_barrier
	ds_read_b128 v[198:201], v181 offset:49152
	ds_read_b128 v[202:205], v181 offset:50176
	ds_read_b128 v[206:209], v181 offset:51200
	ds_read_b128 v[210:213], v181 offset:52224
	ds_read_b128 v[214:217], v181 offset:53248
	ds_read_b128 v[218:221], v181 offset:54272
	ds_read_b128 v[222:225], v181 offset:55296
	ds_read_b128 v[226:229], v181 offset:56320
	global_load_lds_dwordx4 v142, vcc
	s_mov_b32 m0, s58
	s_nop 0
	global_load_lds_dwordx4 v140, vcc
	s_barrier
	s_waitcnt lgkmcnt(0)
	s_setprio 1
	s_waitcnt lgkmcnt(0)
	v_mfma_f32_16x16x32_bf16 v[62:65], v[182:185], v[198:201], v[62:65]
	v_mfma_f32_16x16x32_bf16 v[54:57], v[190:193], v[198:201], v[54:57]
	v_mfma_f32_16x16x32_bf16 v[46:49], v[182:185], v[206:209], v[46:49]
	v_mfma_f32_16x16x32_bf16 v[38:41], v[190:193], v[206:209], v[38:41]
	v_mfma_f32_16x16x32_bf16 v[30:33], v[182:185], v[214:217], v[30:33]
	v_mfma_f32_16x16x32_bf16 v[22:25], v[190:193], v[214:217], v[22:25]
	v_mfma_f32_16x16x32_bf16 v[14:17], v[182:185], v[222:225], v[14:17]
	v_mfma_f32_16x16x32_bf16 v[6:9], v[190:193], v[222:225], v[6:9]
	v_mfma_f32_16x16x32_bf16 v[62:65], v[186:189], v[202:205], v[62:65]
	v_mfma_f32_16x16x32_bf16 v[54:57], v[194:197], v[202:205], v[54:57]
	v_mfma_f32_16x16x32_bf16 v[46:49], v[186:189], v[210:213], v[46:49]
	v_mfma_f32_16x16x32_bf16 v[38:41], v[194:197], v[210:213], v[38:41]
	v_mfma_f32_16x16x32_bf16 v[30:33], v[186:189], v[218:221], v[30:33]
	v_mfma_f32_16x16x32_bf16 v[22:25], v[194:197], v[218:221], v[22:25]
	v_mfma_f32_16x16x32_bf16 v[14:17], v[186:189], v[226:229], v[14:17]
	v_mfma_f32_16x16x32_bf16 v[6:9], v[194:197], v[226:229], v[6:9]
	s_setprio 0
	s_barrier
	s_add_u32 s26, s26, 0x80080
	s_addc_u32 s27, s27, 0
	s_add_i32 s52, s52, s6
	s_mov_b32 m0, s52
	s_nop 0
	global_load_lds_dwordx4 v0, s[26:27]
	s_add_i32 m0, s52, 0x2000
	s_nop 0
	global_load_lds_dwordx4 v138, s[26:27]
	s_waitcnt vmcnt(6)
	s_barrier
	s_setprio 1
	v_mfma_f32_16x16x32_bf16 v[58:61], v[230:233], v[198:201], v[58:61]
	v_mfma_f32_16x16x32_bf16 v[50:53], v[238:241], v[198:201], v[50:53]
	v_mfma_f32_16x16x32_bf16 v[42:45], v[230:233], v[206:209], v[42:45]
	v_mfma_f32_16x16x32_bf16 v[34:37], v[238:241], v[206:209], v[34:37]
	v_mfma_f32_16x16x32_bf16 v[26:29], v[230:233], v[214:217], v[26:29]
	v_mfma_f32_16x16x32_bf16 v[18:21], v[238:241], v[214:217], v[18:21]
	v_mfma_f32_16x16x32_bf16 v[10:13], v[230:233], v[222:225], v[10:13]
	v_mfma_f32_16x16x32_bf16 v[2:5], v[238:241], v[222:225], v[2:5]
	v_mfma_f32_16x16x32_bf16 v[58:61], v[234:237], v[202:205], v[58:61]
	v_mfma_f32_16x16x32_bf16 v[50:53], v[242:245], v[202:205], v[50:53]
	v_mfma_f32_16x16x32_bf16 v[42:45], v[234:237], v[210:213], v[42:45]
	v_mfma_f32_16x16x32_bf16 v[34:37], v[242:245], v[210:213], v[34:37]
	v_mfma_f32_16x16x32_bf16 v[26:29], v[234:237], v[218:221], v[26:29]
	v_mfma_f32_16x16x32_bf16 v[18:21], v[242:245], v[218:221], v[18:21]
	v_mfma_f32_16x16x32_bf16 v[10:13], v[234:237], v[226:229], v[10:13]
	v_mfma_f32_16x16x32_bf16 v[2:5], v[242:245], v[226:229], v[2:5]
	s_setprio 0
	s_add_i32 s66, s66, 2
	s_add_u32 s50, s50, 0x100
	s_addc_u32 s51, s51, 0
	s_add_u32 s64, s64, 0x100
	s_addc_u32 s65, s65, 0
	s_cmp_gt_u32 s66, 29
	s_barrier
	s_cbranch_scc0 .LBB0_108
	v_mul_f32_e32 v134, 0xbfb8aa3b, v126
	v_exp_f32_e32 v134, v134
	s_lshl_b32 s23, s61, 7
	s_or_b32 s23, s23, s56
	s_ashr_i32 s23, s23, 6
	v_add_f32_e32 v134, 1.0, v134
	v_rcp_f32_e32 v134, v134
	s_mul_i32 s26, s60, 0x58
	s_ashr_i32 s43, s23, 31
	s_mul_hi_i32 s27, s60, 0x58
	v_mul_f32_e32 v126, v126, v134
	v_mul_f32_e32 v122, v126, v122
	v_mul_f32_e32 v126, 0xbfb8aa3b, v118
	v_exp_f32_e32 v126, v126
	s_add_u32 s26, s26, s23
	s_addc_u32 s27, s27, s43
	s_lshl_b64 s[26:27], s[26:27], 15
	v_add_f32_e32 v126, 1.0, v126
	v_rcp_f32_e32 v126, v126
	v_lshl_add_u64 v[166:167], v[144:145], 0, s[26:27]
	s_and_b64 vcc, exec, s[38:39]
	s_mov_b32 s61, s22
	v_mul_f32_e32 v118, v118, v126
	v_mul_f32_e32 v126, v118, v114
	v_mul_f32_e32 v114, 0xbfb8aa3b, v127
	v_mul_f32_e32 v118, 0xbfb8aa3b, v119
	v_exp_f32_e32 v114, v114
	v_exp_f32_e32 v118, v118
	s_mov_b32 s60, s42
	s_mov_b64 s[26:27], s[24:25]
	v_add_f32_e32 v114, 1.0, v114
	v_add_f32_e32 v118, 1.0, v118
	v_rcp_f32_e32 v114, v114
	v_rcp_f32_e32 v118, v118
	s_mov_b64 s[50:51], s[48:49]
	v_readlane_b32 s70, v254, 38
	v_mul_f32_e32 v114, v127, v114
	v_mul_f32_e32 v118, v119, v118
	v_mul_f32_e32 v114, v114, v123
	v_mul_f32_e32 v123, v118, v115
	v_mul_f32_e32 v118, 0xbfb8aa3b, v120
	v_exp_f32_e32 v118, v118
	v_mul_f32_e32 v115, 0xbfb8aa3b, v128
	v_exp_f32_e32 v115, v115
	v_cvt_pk_bf16_f32 v114, v122, v114
	v_add_f32_e32 v118, 1.0, v118
	v_rcp_f32_e32 v118, v118
	v_add_f32_e32 v115, 1.0, v115
	v_rcp_f32_e32 v115, v115
	v_mul_f32_e32 v118, v120, v118
	v_mul_f32_e32 v120, v118, v116
	v_mul_f32_e32 v116, 0xbfb8aa3b, v129
	v_mul_f32_e32 v118, 0xbfb8aa3b, v121
	v_exp_f32_e32 v116, v116
	v_exp_f32_e32 v118, v118
	v_mul_f32_e32 v115, v128, v115
	v_mul_f32_e32 v115, v115, v124
	v_add_f32_e32 v116, 1.0, v116
	v_add_f32_e32 v118, 1.0, v118
	v_rcp_f32_e32 v116, v116
	v_rcp_f32_e32 v118, v118
	v_mul_f32_e32 v116, v129, v116
	v_mul_f32_e32 v118, v121, v118
	v_mul_f32_e32 v116, v116, v125
	v_mul_f32_e32 v117, v118, v117
	v_lshl_add_u64 v[118:119], v[166:167], 0, v[146:147]
	v_cvt_pk_bf16_f32 v115, v115, v116
	v_cvt_pk_bf16_f32 v116, v126, v123
	v_cvt_pk_bf16_f32 v117, v120, v117
	global_store_dwordx4 v[118:119], v[114:117], off
	s_nop 1
	v_mul_f32_e32 v114, 0xbfb8aa3b, v110
	v_exp_f32_e32 v114, v114
	s_nop 0
	v_add_f32_e32 v114, 1.0, v114
	v_rcp_f32_e32 v114, v114
	s_nop 0
	v_mul_f32_e32 v110, v110, v114
	v_mul_f32_e32 v106, v110, v106
	v_mul_f32_e32 v110, 0xbfb8aa3b, v102
	v_exp_f32_e32 v110, v110
	s_nop 0
	v_add_f32_e32 v110, 1.0, v110
	v_rcp_f32_e32 v110, v110
	s_nop 0
	v_mul_f32_e32 v102, v102, v110
	v_mul_f32_e32 v110, v102, v98
	v_mul_f32_e32 v98, 0xbfb8aa3b, v111
	v_mul_f32_e32 v102, 0xbfb8aa3b, v103
	v_exp_f32_e32 v98, v98
	v_exp_f32_e32 v102, v102
	v_add_f32_e32 v98, 1.0, v98
	v_add_f32_e32 v102, 1.0, v102
	v_rcp_f32_e32 v98, v98
	v_rcp_f32_e32 v102, v102
	v_mul_f32_e32 v98, v111, v98
	v_mul_f32_e32 v102, v103, v102
	v_mul_f32_e32 v98, v98, v107
	v_mul_f32_e32 v107, v102, v99
	v_mul_f32_e32 v102, 0xbfb8aa3b, v104
	v_exp_f32_e32 v102, v102
	v_mul_f32_e32 v99, 0xbfb8aa3b, v112
	v_exp_f32_e32 v99, v99
	v_cvt_pk_bf16_f32 v98, v106, v98
	v_add_f32_e32 v102, 1.0, v102
	v_rcp_f32_e32 v102, v102
	v_add_f32_e32 v99, 1.0, v99
	v_rcp_f32_e32 v99, v99
	v_mul_f32_e32 v102, v104, v102
	v_mul_f32_e32 v104, v102, v100
	v_mul_f32_e32 v100, 0xbfb8aa3b, v113
	v_mul_f32_e32 v102, 0xbfb8aa3b, v105
	v_exp_f32_e32 v100, v100
	v_exp_f32_e32 v102, v102
	v_mul_f32_e32 v99, v112, v99
	v_mul_f32_e32 v99, v99, v108
	v_add_f32_e32 v100, 1.0, v100
	v_add_f32_e32 v102, 1.0, v102
	v_rcp_f32_e32 v100, v100
	v_rcp_f32_e32 v102, v102
	v_mul_f32_e32 v100, v113, v100
	v_mul_f32_e32 v102, v105, v102
	v_mul_f32_e32 v100, v100, v109
	v_mul_f32_e32 v101, v102, v101
	v_lshl_add_u64 v[102:103], v[166:167], 0, v[148:149]
	v_cvt_pk_bf16_f32 v99, v99, v100
	v_cvt_pk_bf16_f32 v100, v110, v107
	v_cvt_pk_bf16_f32 v101, v104, v101
	global_store_dwordx4 v[102:103], v[98:101], off
	s_nop 1
	v_mul_f32_e32 v98, 0xbfb8aa3b, v94
	v_exp_f32_e32 v98, v98
	s_nop 0
	v_add_f32_e32 v98, 1.0, v98
	v_rcp_f32_e32 v98, v98
	s_nop 0
	v_mul_f32_e32 v94, v94, v98
	v_mul_f32_e32 v90, v94, v90
	v_mul_f32_e32 v94, 0xbfb8aa3b, v86
	v_exp_f32_e32 v94, v94
	s_nop 0
	v_add_f32_e32 v94, 1.0, v94
	v_rcp_f32_e32 v94, v94
	s_nop 0
	v_mul_f32_e32 v86, v86, v94
	v_mul_f32_e32 v94, v86, v82
	v_mul_f32_e32 v82, 0xbfb8aa3b, v95
	v_mul_f32_e32 v86, 0xbfb8aa3b, v87
	v_exp_f32_e32 v82, v82
	v_exp_f32_e32 v86, v86
	v_add_f32_e32 v82, 1.0, v82
	v_add_f32_e32 v86, 1.0, v86
	v_rcp_f32_e32 v82, v82
	v_rcp_f32_e32 v86, v86
	v_mul_f32_e32 v82, v95, v82
	v_mul_f32_e32 v86, v87, v86
	v_mul_f32_e32 v82, v82, v91
	v_mul_f32_e32 v91, v86, v83
	v_mul_f32_e32 v86, 0xbfb8aa3b, v88
	v_exp_f32_e32 v86, v86
	v_mul_f32_e32 v83, 0xbfb8aa3b, v96
	v_exp_f32_e32 v83, v83
	v_cvt_pk_bf16_f32 v82, v90, v82
	v_add_f32_e32 v86, 1.0, v86
	v_rcp_f32_e32 v86, v86
	v_add_f32_e32 v83, 1.0, v83
	v_rcp_f32_e32 v83, v83
	v_mul_f32_e32 v86, v88, v86
	v_mul_f32_e32 v88, v86, v84
	v_mul_f32_e32 v84, 0xbfb8aa3b, v97
	v_mul_f32_e32 v86, 0xbfb8aa3b, v89
	v_exp_f32_e32 v84, v84
	v_exp_f32_e32 v86, v86
	v_mul_f32_e32 v83, v96, v83
	v_mul_f32_e32 v83, v83, v92
	v_add_f32_e32 v84, 1.0, v84
	v_add_f32_e32 v86, 1.0, v86
	v_rcp_f32_e32 v84, v84
	v_rcp_f32_e32 v86, v86
	v_mul_f32_e32 v84, v97, v84
	v_mul_f32_e32 v86, v89, v86
	v_mul_f32_e32 v84, v84, v93
	v_mul_f32_e32 v85, v86, v85
	v_lshl_add_u64 v[86:87], v[166:167], 0, v[150:151]
	v_cvt_pk_bf16_f32 v83, v83, v84
	v_cvt_pk_bf16_f32 v84, v94, v91
	v_cvt_pk_bf16_f32 v85, v88, v85
	global_store_dwordx4 v[86:87], v[82:85], off
	s_nop 1
	v_mul_f32_e32 v82, 0xbfb8aa3b, v78
	v_exp_f32_e32 v82, v82
	s_nop 0
	v_add_f32_e32 v82, 1.0, v82
	v_rcp_f32_e32 v82, v82
	s_nop 0
	v_mul_f32_e32 v78, v78, v82
	v_mul_f32_e32 v74, v78, v74
	v_mul_f32_e32 v78, 0xbfb8aa3b, v70
	v_exp_f32_e32 v78, v78
	s_nop 0
	v_add_f32_e32 v78, 1.0, v78
	v_rcp_f32_e32 v78, v78
	s_nop 0
	v_mul_f32_e32 v70, v70, v78
	v_mul_f32_e32 v78, v70, v66
	v_mul_f32_e32 v66, 0xbfb8aa3b, v79
	v_mul_f32_e32 v70, 0xbfb8aa3b, v71
	v_exp_f32_e32 v66, v66
	v_exp_f32_e32 v70, v70
	v_add_f32_e32 v66, 1.0, v66
	v_add_f32_e32 v70, 1.0, v70
	v_rcp_f32_e32 v66, v66
	v_rcp_f32_e32 v70, v70
	v_mul_f32_e32 v66, v79, v66
	v_mul_f32_e32 v70, v71, v70
	v_mul_f32_e32 v66, v66, v75
	v_mul_f32_e32 v75, v70, v67
	v_mul_f32_e32 v70, 0xbfb8aa3b, v72
	v_exp_f32_e32 v70, v70
	v_mul_f32_e32 v67, 0xbfb8aa3b, v80
	v_exp_f32_e32 v67, v67
	v_cvt_pk_bf16_f32 v66, v74, v66
	v_add_f32_e32 v70, 1.0, v70
	v_rcp_f32_e32 v70, v70
	v_add_f32_e32 v67, 1.0, v67
	v_rcp_f32_e32 v67, v67
	v_mul_f32_e32 v70, v72, v70
	v_mul_f32_e32 v72, v70, v68
	v_mul_f32_e32 v68, 0xbfb8aa3b, v81
	v_mul_f32_e32 v70, 0xbfb8aa3b, v73
	v_exp_f32_e32 v68, v68
	v_exp_f32_e32 v70, v70
	v_mul_f32_e32 v67, v80, v67
	v_mul_f32_e32 v67, v67, v76
	v_add_f32_e32 v68, 1.0, v68
	v_add_f32_e32 v70, 1.0, v70
	v_rcp_f32_e32 v68, v68
	v_rcp_f32_e32 v70, v70
	v_mul_f32_e32 v68, v81, v68
	v_mul_f32_e32 v70, v73, v70
	v_mul_f32_e32 v68, v68, v77
	v_mul_f32_e32 v69, v70, v69
	v_lshl_add_u64 v[70:71], v[166:167], 0, v[152:153]
	v_cvt_pk_bf16_f32 v67, v67, v68
	v_cvt_pk_bf16_f32 v68, v78, v75
	v_cvt_pk_bf16_f32 v69, v72, v69
	global_store_dwordx4 v[70:71], v[66:69], off
	s_nop 1
	v_mul_f32_e32 v66, 0xbfb8aa3b, v62
	v_exp_f32_e32 v66, v66
	s_nop 0
	v_add_f32_e32 v66, 1.0, v66
	v_rcp_f32_e32 v66, v66
	s_nop 0
	v_mul_f32_e32 v62, v62, v66
	v_mul_f32_e32 v58, v62, v58
	v_mul_f32_e32 v62, 0xbfb8aa3b, v54
	v_exp_f32_e32 v62, v62
	s_nop 0
	v_add_f32_e32 v62, 1.0, v62
	v_rcp_f32_e32 v62, v62
	s_nop 0
	v_mul_f32_e32 v54, v54, v62
	v_mul_f32_e32 v62, v54, v50
	v_mul_f32_e32 v50, 0xbfb8aa3b, v63
	v_mul_f32_e32 v54, 0xbfb8aa3b, v55
	v_exp_f32_e32 v50, v50
	v_exp_f32_e32 v54, v54
	v_add_f32_e32 v50, 1.0, v50
	v_add_f32_e32 v54, 1.0, v54
	v_rcp_f32_e32 v50, v50
	v_rcp_f32_e32 v54, v54
	v_mul_f32_e32 v50, v63, v50
	v_mul_f32_e32 v54, v55, v54
	v_mul_f32_e32 v50, v50, v59
	v_mul_f32_e32 v59, v54, v51
	v_mul_f32_e32 v54, 0xbfb8aa3b, v56
	v_exp_f32_e32 v54, v54
	v_mul_f32_e32 v51, 0xbfb8aa3b, v64
	v_exp_f32_e32 v51, v51
	v_cvt_pk_bf16_f32 v50, v58, v50
	v_add_f32_e32 v54, 1.0, v54
	v_rcp_f32_e32 v54, v54
	v_add_f32_e32 v51, 1.0, v51
	v_rcp_f32_e32 v51, v51
	v_mul_f32_e32 v54, v56, v54
	v_mul_f32_e32 v56, v54, v52
	v_mul_f32_e32 v52, 0xbfb8aa3b, v65
	v_mul_f32_e32 v54, 0xbfb8aa3b, v57
	v_exp_f32_e32 v52, v52
	v_exp_f32_e32 v54, v54
	v_mul_f32_e32 v51, v64, v51
	v_mul_f32_e32 v51, v51, v60
	v_add_f32_e32 v52, 1.0, v52
	v_add_f32_e32 v54, 1.0, v54
	v_rcp_f32_e32 v52, v52
	v_rcp_f32_e32 v54, v54
	v_mul_f32_e32 v52, v65, v52
	v_mul_f32_e32 v54, v57, v54
	v_mul_f32_e32 v52, v52, v61
	v_mul_f32_e32 v53, v54, v53
	v_lshl_add_u64 v[54:55], v[166:167], 0, v[154:155]
	v_cvt_pk_bf16_f32 v51, v51, v52
	v_cvt_pk_bf16_f32 v52, v62, v59
	v_cvt_pk_bf16_f32 v53, v56, v53
	global_store_dwordx4 v[54:55], v[50:53], off
	s_nop 1
	v_mul_f32_e32 v50, 0xbfb8aa3b, v46
	v_exp_f32_e32 v50, v50
	s_nop 0
	v_add_f32_e32 v50, 1.0, v50
	v_rcp_f32_e32 v50, v50
	s_nop 0
	v_mul_f32_e32 v46, v46, v50
	v_mul_f32_e32 v42, v46, v42
	v_mul_f32_e32 v46, 0xbfb8aa3b, v38
	v_exp_f32_e32 v46, v46
	s_nop 0
	v_add_f32_e32 v46, 1.0, v46
	v_rcp_f32_e32 v46, v46
	s_nop 0
	v_mul_f32_e32 v38, v38, v46
	v_mul_f32_e32 v46, v38, v34
	v_mul_f32_e32 v34, 0xbfb8aa3b, v47
	v_mul_f32_e32 v38, 0xbfb8aa3b, v39
	v_exp_f32_e32 v34, v34
	v_exp_f32_e32 v38, v38
	v_add_f32_e32 v34, 1.0, v34
	v_add_f32_e32 v38, 1.0, v38
	v_rcp_f32_e32 v34, v34
	v_rcp_f32_e32 v38, v38
	v_mul_f32_e32 v34, v47, v34
	v_mul_f32_e32 v38, v39, v38
	v_mul_f32_e32 v34, v34, v43
	v_mul_f32_e32 v43, v38, v35
	v_mul_f32_e32 v38, 0xbfb8aa3b, v40
	v_exp_f32_e32 v38, v38
	v_mul_f32_e32 v35, 0xbfb8aa3b, v48
	v_exp_f32_e32 v35, v35
	v_cvt_pk_bf16_f32 v34, v42, v34
	v_add_f32_e32 v38, 1.0, v38
	v_rcp_f32_e32 v38, v38
	v_add_f32_e32 v35, 1.0, v35
	v_rcp_f32_e32 v35, v35
	v_mul_f32_e32 v38, v40, v38
	v_mul_f32_e32 v40, v38, v36
	v_mul_f32_e32 v36, 0xbfb8aa3b, v49
	v_mul_f32_e32 v38, 0xbfb8aa3b, v41
	v_exp_f32_e32 v36, v36
	v_exp_f32_e32 v38, v38
	v_mul_f32_e32 v35, v48, v35
	v_mul_f32_e32 v35, v35, v44
	v_add_f32_e32 v36, 1.0, v36
	v_add_f32_e32 v38, 1.0, v38
	v_rcp_f32_e32 v36, v36
	v_rcp_f32_e32 v38, v38
	v_mul_f32_e32 v36, v49, v36
	v_mul_f32_e32 v38, v41, v38
	v_mul_f32_e32 v36, v36, v45
	v_mul_f32_e32 v37, v38, v37
	v_lshl_add_u64 v[38:39], v[166:167], 0, v[156:157]
	v_cvt_pk_bf16_f32 v35, v35, v36
	v_cvt_pk_bf16_f32 v36, v46, v43
	v_cvt_pk_bf16_f32 v37, v40, v37
	global_store_dwordx4 v[38:39], v[34:37], off
	s_nop 1
	v_mul_f32_e32 v34, 0xbfb8aa3b, v30
	v_exp_f32_e32 v34, v34
	s_nop 0
	v_add_f32_e32 v34, 1.0, v34
	v_rcp_f32_e32 v34, v34
	s_nop 0
	v_mul_f32_e32 v30, v30, v34
	v_mul_f32_e32 v26, v30, v26
	v_mul_f32_e32 v30, 0xbfb8aa3b, v22
	v_exp_f32_e32 v30, v30
	s_nop 0
	v_add_f32_e32 v30, 1.0, v30
	v_rcp_f32_e32 v30, v30
	s_nop 0
	v_mul_f32_e32 v22, v22, v30
	v_mul_f32_e32 v30, v22, v18
	v_mul_f32_e32 v18, 0xbfb8aa3b, v31
	v_mul_f32_e32 v22, 0xbfb8aa3b, v23
	v_exp_f32_e32 v18, v18
	v_exp_f32_e32 v22, v22
	v_add_f32_e32 v18, 1.0, v18
	v_add_f32_e32 v22, 1.0, v22
	v_rcp_f32_e32 v18, v18
	v_rcp_f32_e32 v22, v22
	v_mul_f32_e32 v18, v31, v18
	v_mul_f32_e32 v22, v23, v22
	v_mul_f32_e32 v18, v18, v27
	v_mul_f32_e32 v27, v22, v19
	v_mul_f32_e32 v22, 0xbfb8aa3b, v24
	v_exp_f32_e32 v22, v22
	v_mul_f32_e32 v19, 0xbfb8aa3b, v32
	v_exp_f32_e32 v19, v19
	v_cvt_pk_bf16_f32 v18, v26, v18
	v_add_f32_e32 v22, 1.0, v22
	v_rcp_f32_e32 v22, v22
	v_add_f32_e32 v19, 1.0, v19
	v_rcp_f32_e32 v19, v19
	v_mul_f32_e32 v22, v24, v22
	v_mul_f32_e32 v24, v22, v20
	v_mul_f32_e32 v20, 0xbfb8aa3b, v33
	v_mul_f32_e32 v22, 0xbfb8aa3b, v25
	v_exp_f32_e32 v20, v20
	v_exp_f32_e32 v22, v22
	v_mul_f32_e32 v19, v32, v19
	v_mul_f32_e32 v19, v19, v28
	v_add_f32_e32 v20, 1.0, v20
	v_add_f32_e32 v22, 1.0, v22
	v_rcp_f32_e32 v20, v20
	v_rcp_f32_e32 v22, v22
	v_mul_f32_e32 v20, v33, v20
	v_mul_f32_e32 v22, v25, v22
	v_mul_f32_e32 v20, v20, v29
	v_mul_f32_e32 v21, v22, v21
	v_lshl_add_u64 v[22:23], v[166:167], 0, v[158:159]
	v_cvt_pk_bf16_f32 v19, v19, v20
	v_cvt_pk_bf16_f32 v20, v30, v27
	v_cvt_pk_bf16_f32 v21, v24, v21
	global_store_dwordx4 v[22:23], v[18:21], off
	s_nop 1
	v_mul_f32_e32 v18, 0xbfb8aa3b, v14
	v_exp_f32_e32 v18, v18
	s_nop 0
	v_add_f32_e32 v18, 1.0, v18
	v_rcp_f32_e32 v18, v18
	s_nop 0
	v_mul_f32_e32 v14, v14, v18
	v_mul_f32_e32 v10, v14, v10
	v_mul_f32_e32 v14, 0xbfb8aa3b, v6
	v_exp_f32_e32 v14, v14
	s_nop 0
	v_add_f32_e32 v14, 1.0, v14
	v_rcp_f32_e32 v14, v14
	s_nop 0
	v_mul_f32_e32 v6, v6, v14
	v_mul_f32_e32 v14, v6, v2
	v_mul_f32_e32 v2, 0xbfb8aa3b, v15
	v_mul_f32_e32 v6, 0xbfb8aa3b, v7
	v_exp_f32_e32 v2, v2
	v_exp_f32_e32 v6, v6
	v_add_f32_e32 v2, 1.0, v2
	v_add_f32_e32 v6, 1.0, v6
	v_rcp_f32_e32 v2, v2
	v_rcp_f32_e32 v6, v6
	v_mul_f32_e32 v2, v15, v2
	v_mul_f32_e32 v6, v7, v6
	v_mul_f32_e32 v2, v2, v11
	v_mul_f32_e32 v11, v6, v3
	v_mul_f32_e32 v6, 0xbfb8aa3b, v8
	v_exp_f32_e32 v6, v6
	v_mul_f32_e32 v3, 0xbfb8aa3b, v16
	v_exp_f32_e32 v3, v3
	v_cvt_pk_bf16_f32 v2, v10, v2
	v_add_f32_e32 v6, 1.0, v6
	v_rcp_f32_e32 v6, v6
	v_add_f32_e32 v3, 1.0, v3
	v_rcp_f32_e32 v3, v3
	v_mul_f32_e32 v6, v8, v6
	v_mul_f32_e32 v8, v6, v4
	v_mul_f32_e32 v4, 0xbfb8aa3b, v17
	v_mul_f32_e32 v6, 0xbfb8aa3b, v9
	v_exp_f32_e32 v4, v4
	v_exp_f32_e32 v6, v6
	v_mul_f32_e32 v3, v16, v3
	v_mul_f32_e32 v3, v3, v12
	v_add_f32_e32 v4, 1.0, v4
	v_add_f32_e32 v6, 1.0, v6
	v_rcp_f32_e32 v4, v4
	v_rcp_f32_e32 v6, v6
	v_mul_f32_e32 v4, v17, v4
	v_mul_f32_e32 v6, v9, v6
	v_mul_f32_e32 v4, v4, v13
	v_mul_f32_e32 v5, v6, v5
	v_lshl_add_u64 v[6:7], v[166:167], 0, v[160:161]
	v_cvt_pk_bf16_f32 v3, v3, v4
	v_cvt_pk_bf16_f32 v4, v14, v11
	v_cvt_pk_bf16_f32 v5, v8, v5
	global_store_dwordx4 v[6:7], v[2:5], off
	s_cbranch_vccz .LBB0_105
	s_waitcnt vmcnt(0)
	v_readlane_b32 s50, v254, 28
	v_readlane_b32 s56, v254, 30
	v_readlane_b32 s60, v254, 39
	s_cmpk_gt_u32 s4, 0xff
	v_readlane_b32 s51, v254, 29
	v_readlane_b32 s57, v254, 31
	v_readlane_b32 s61, v254, 40
	s_mov_b64 s[58:59], s[84:85]
	s_cbranch_scc1 .LBB0_112
	s_barrier

.LBB0_182:
	s_add_u32 s26, s38, 0x4000
	s_addc_u32 s27, s39, 0
	s_cmpk_eq_i32 s61, 0x54
	s_cselect_b32 s48, s0, s26
	s_cselect_b32 s49, s1, s27
	s_cselect_b32 s26, s24, s59
	s_cselect_b32 s27, s25, s60
	s_add_u32 s42, s48, 0x8000
	s_addc_u32 s43, s49, 0
	s_add_i32 s62, 0, 0x10000
	v_add_u32_e32 v134, s62, v155
	ds_read_b128 v[148:151], v134
	ds_read_b128 v[158:161], v134 offset:1024
	ds_read_b128 v[162:165], v134 offset:2048
	ds_read_b128 v[180:183], v134 offset:3072
	s_add_i32 m0, s7, 0xc000
	ds_read_b128 v[184:187], v157
	ds_read_b128 v[188:191], v157 offset:1024
	ds_read_b128 v[192:195], v157 offset:2048
	ds_read_b128 v[196:199], v157 offset:3072
	ds_read_b128 v[200:203], v157 offset:4096
	ds_read_b128 v[204:207], v157 offset:5120
	ds_read_b128 v[208:211], v157 offset:6144
	ds_read_b128 v[212:215], v157 offset:7168
	global_load_lds_dwordx4 v144, s[38:39]
	s_add_i32 m0, s7, 0xe000
	s_nop 0
	global_load_lds_dwordx4 v146, s[38:39]
	s_waitcnt lgkmcnt(8)
	s_barrier
	s_waitcnt lgkmcnt(0)
	s_setprio 1
	s_waitcnt lgkmcnt(0)
	v_mfma_f32_16x16x32_bf16 v[126:129], v[148:151], v[184:187], v[126:129]
	v_mfma_f32_16x16x32_bf16 v[122:125], v[162:165], v[184:187], v[122:125]
	v_mfma_f32_16x16x32_bf16 v[110:113], v[148:151], v[192:195], v[110:113]
	v_mfma_f32_16x16x32_bf16 v[106:109], v[162:165], v[192:195], v[106:109]
	v_mfma_f32_16x16x32_bf16 v[94:97], v[148:151], v[200:203], v[94:97]
	v_mfma_f32_16x16x32_bf16 v[90:93], v[162:165], v[200:203], v[90:93]
	v_mfma_f32_16x16x32_bf16 v[78:81], v[148:151], v[208:211], v[78:81]
	v_mfma_f32_16x16x32_bf16 v[74:77], v[162:165], v[208:211], v[74:77]
	v_mfma_f32_16x16x32_bf16 v[126:129], v[158:161], v[188:191], v[126:129]
	v_mfma_f32_16x16x32_bf16 v[122:125], v[180:183], v[188:191], v[122:125]
	v_mfma_f32_16x16x32_bf16 v[110:113], v[158:161], v[196:199], v[110:113]
	v_mfma_f32_16x16x32_bf16 v[106:109], v[180:183], v[196:199], v[106:109]
	v_mfma_f32_16x16x32_bf16 v[94:97], v[158:161], v[204:207], v[94:97]
	v_mfma_f32_16x16x32_bf16 v[90:93], v[180:183], v[204:207], v[90:93]
	v_mfma_f32_16x16x32_bf16 v[78:81], v[158:161], v[212:215], v[78:81]
	v_mfma_f32_16x16x32_bf16 v[74:77], v[180:183], v[212:215], v[74:77]
	s_setprio 0
	s_barrier
	s_add_i32 s64, 0, 0x14000
	v_add_u32_e32 v134, s64, v155
	s_add_i32 s62, s62, s6
	ds_read_b128 v[216:219], v134
	ds_read_b128 v[220:223], v134 offset:1024
	ds_read_b128 v[224:227], v134 offset:2048
	ds_read_b128 v[228:231], v134 offset:3072
	s_mov_b32 m0, s62
	global_load_lds_dwordx4 v0, s[26:27]
	s_add_i32 m0, s62, 0x2000
	s_nop 0
	global_load_lds_dwordx4 v138, s[26:27]
	s_barrier
	s_waitcnt lgkmcnt(0)
	s_setprio 1
	s_waitcnt lgkmcnt(0)
	v_mfma_f32_16x16x32_bf16 v[118:121], v[216:219], v[184:187], v[118:121]
	v_mfma_f32_16x16x32_bf16 v[114:117], v[224:227], v[184:187], v[114:117]
	v_mfma_f32_16x16x32_bf16 v[102:105], v[216:219], v[192:195], v[102:105]
	v_mfma_f32_16x16x32_bf16 v[98:101], v[224:227], v[192:195], v[98:101]
	v_mfma_f32_16x16x32_bf16 v[86:89], v[216:219], v[200:203], v[86:89]
	v_mfma_f32_16x16x32_bf16 v[82:85], v[224:227], v[200:203], v[82:85]
	v_mfma_f32_16x16x32_bf16 v[70:73], v[216:219], v[208:211], v[70:73]
	v_mfma_f32_16x16x32_bf16 v[66:69], v[224:227], v[208:211], v[66:69]
	v_mfma_f32_16x16x32_bf16 v[118:121], v[220:223], v[188:191], v[118:121]
	v_mfma_f32_16x16x32_bf16 v[114:117], v[228:231], v[188:191], v[114:117]
	v_mfma_f32_16x16x32_bf16 v[102:105], v[220:223], v[196:199], v[102:105]
	v_mfma_f32_16x16x32_bf16 v[98:101], v[228:231], v[196:199], v[98:101]
	v_mfma_f32_16x16x32_bf16 v[86:89], v[220:223], v[204:207], v[86:89]
	v_mfma_f32_16x16x32_bf16 v[82:85], v[228:231], v[204:207], v[82:85]
	v_mfma_f32_16x16x32_bf16 v[70:73], v[220:223], v[212:215], v[70:73]
	v_mfma_f32_16x16x32_bf16 v[66:69], v[228:231], v[212:215], v[66:69]
	s_setprio 0
	s_mov_b32 m0, s7
	s_barrier
	ds_read_b128 v[184:187], v157 offset:16384
	ds_read_b128 v[188:191], v157 offset:17408
	ds_read_b128 v[192:195], v157 offset:18432
	ds_read_b128 v[196:199], v157 offset:19456
	ds_read_b128 v[200:203], v157 offset:20480
	ds_read_b128 v[204:207], v157 offset:21504
	ds_read_b128 v[208:211], v157 offset:22528
	ds_read_b128 v[212:215], v157 offset:23552
	global_load_lds_dwordx4 v142, s[48:49]
	s_mov_b32 m0, s14
	s_nop 0
	global_load_lds_dwordx4 v140, s[48:49]
	s_barrier
	s_waitcnt lgkmcnt(0)
	s_setprio 1
	s_waitcnt lgkmcnt(0)
	v_mfma_f32_16x16x32_bf16 v[62:65], v[148:151], v[184:187], v[62:65]
	v_mfma_f32_16x16x32_bf16 v[58:61], v[162:165], v[184:187], v[58:61]
	v_mfma_f32_16x16x32_bf16 v[46:49], v[148:151], v[192:195], v[46:49]
	v_mfma_f32_16x16x32_bf16 v[42:45], v[162:165], v[192:195], v[42:45]
	v_mfma_f32_16x16x32_bf16 v[30:33], v[148:151], v[200:203], v[30:33]
	v_mfma_f32_16x16x32_bf16 v[26:29], v[162:165], v[200:203], v[26:29]
	v_mfma_f32_16x16x32_bf16 v[14:17], v[148:151], v[208:211], v[14:17]
	v_mfma_f32_16x16x32_bf16 v[10:13], v[162:165], v[208:211], v[10:13]
	v_mfma_f32_16x16x32_bf16 v[62:65], v[158:161], v[188:191], v[62:65]
	v_mfma_f32_16x16x32_bf16 v[58:61], v[180:183], v[188:191], v[58:61]
	v_mfma_f32_16x16x32_bf16 v[46:49], v[158:161], v[196:199], v[46:49]
	v_mfma_f32_16x16x32_bf16 v[42:45], v[180:183], v[196:199], v[42:45]
	v_mfma_f32_16x16x32_bf16 v[30:33], v[158:161], v[204:207], v[30:33]
	v_mfma_f32_16x16x32_bf16 v[26:29], v[180:183], v[204:207], v[26:29]
	v_mfma_f32_16x16x32_bf16 v[14:17], v[158:161], v[212:215], v[14:17]
	v_mfma_f32_16x16x32_bf16 v[10:13], v[180:183], v[212:215], v[10:13]
	s_setprio 0
	s_barrier
	s_add_u32 s62, s26, 0x160000
	s_addc_u32 s63, s27, 0
	s_add_i32 s64, s64, s6
	s_mov_b32 m0, s64
	s_nop 0
	global_load_lds_dwordx4 v0, s[62:63]
	s_add_i32 m0, s64, 0x2000
	s_nop 0
	global_load_lds_dwordx4 v138, s[62:63]
	s_waitcnt vmcnt(6)
	s_barrier
	s_setprio 1
	v_mfma_f32_16x16x32_bf16 v[54:57], v[216:219], v[184:187], v[54:57]
	v_mfma_f32_16x16x32_bf16 v[50:53], v[224:227], v[184:187], v[50:53]
	v_mfma_f32_16x16x32_bf16 v[38:41], v[216:219], v[192:195], v[38:41]
	v_mfma_f32_16x16x32_bf16 v[34:37], v[224:227], v[192:195], v[34:37]
	v_mfma_f32_16x16x32_bf16 v[22:25], v[216:219], v[200:203], v[22:25]
	v_mfma_f32_16x16x32_bf16 v[18:21], v[224:227], v[200:203], v[18:21]
	v_mfma_f32_16x16x32_bf16 v[6:9], v[216:219], v[208:211], v[6:9]
	v_mfma_f32_16x16x32_bf16 v[2:5], v[224:227], v[208:211], v[2:5]
	v_mfma_f32_16x16x32_bf16 v[54:57], v[220:223], v[188:191], v[54:57]
	v_mfma_f32_16x16x32_bf16 v[50:53], v[228:231], v[188:191], v[50:53]
	v_mfma_f32_16x16x32_bf16 v[38:41], v[220:223], v[196:199], v[38:41]
	v_mfma_f32_16x16x32_bf16 v[34:37], v[228:231], v[196:199], v[34:37]
	v_mfma_f32_16x16x32_bf16 v[22:25], v[220:223], v[204:207], v[22:25]
	v_mfma_f32_16x16x32_bf16 v[18:21], v[228:231], v[204:207], v[18:21]
	v_mfma_f32_16x16x32_bf16 v[6:9], v[220:223], v[212:215], v[6:9]
	v_mfma_f32_16x16x32_bf16 v[2:5], v[228:231], v[212:215], v[2:5]
	s_setprio 0
	s_add_i32 s62, 0, 0x18000
	v_add_u32_e32 v166, s62, v155
	s_barrier
	ds_read_b128 v[148:151], v166
	ds_read_b128 v[158:161], v166 offset:1024
	ds_read_b128 v[162:165], v166 offset:2048
	ds_read_b128 v[180:183], v166 offset:3072
	s_add_u32 s48, s48, 0x4000
	s_addc_u32 s49, s49, 0
	s_mov_b32 m0, s50
	ds_read_b128 v[184:187], v157 offset:32768
	ds_read_b128 v[188:191], v157 offset:33792
	ds_read_b128 v[192:195], v157 offset:34816
	ds_read_b128 v[196:199], v157 offset:35840
	ds_read_b128 v[200:203], v157 offset:36864
	ds_read_b128 v[204:207], v157 offset:37888
	ds_read_b128 v[208:211], v157 offset:38912
	ds_read_b128 v[212:215], v157 offset:39936
	global_load_lds_dwordx4 v142, s[48:49]
	s_mov_b32 m0, s51
	s_nop 0
	global_load_lds_dwordx4 v140, s[48:49]
	s_waitcnt lgkmcnt(8)
	s_barrier
	s_waitcnt lgkmcnt(0)
	s_setprio 1
	s_waitcnt lgkmcnt(0)
	v_mfma_f32_16x16x32_bf16 v[126:129], v[148:151], v[184:187], v[126:129]
	v_mfma_f32_16x16x32_bf16 v[122:125], v[162:165], v[184:187], v[122:125]
	v_mfma_f32_16x16x32_bf16 v[110:113], v[148:151], v[192:195], v[110:113]
	v_mfma_f32_16x16x32_bf16 v[106:109], v[162:165], v[192:195], v[106:109]
	v_mfma_f32_16x16x32_bf16 v[94:97], v[148:151], v[200:203], v[94:97]
	v_mfma_f32_16x16x32_bf16 v[90:93], v[162:165], v[200:203], v[90:93]
	v_mfma_f32_16x16x32_bf16 v[78:81], v[148:151], v[208:211], v[78:81]
	v_mfma_f32_16x16x32_bf16 v[74:77], v[162:165], v[208:211], v[74:77]
	v_mfma_f32_16x16x32_bf16 v[126:129], v[158:161], v[188:191], v[126:129]
	v_mfma_f32_16x16x32_bf16 v[122:125], v[180:183], v[188:191], v[122:125]
	v_mfma_f32_16x16x32_bf16 v[110:113], v[158:161], v[196:199], v[110:113]
	v_mfma_f32_16x16x32_bf16 v[106:109], v[180:183], v[196:199], v[106:109]
	v_mfma_f32_16x16x32_bf16 v[94:97], v[158:161], v[204:207], v[94:97]
	v_mfma_f32_16x16x32_bf16 v[90:93], v[180:183], v[204:207], v[90:93]
	v_mfma_f32_16x16x32_bf16 v[78:81], v[158:161], v[212:215], v[78:81]
	v_mfma_f32_16x16x32_bf16 v[74:77], v[180:183], v[212:215], v[74:77]
	s_setprio 0
	s_barrier
	s_add_i32 s48, 0, 0x1c000
	s_add_i32 s49, s62, s6
	v_add_u32_e32 v166, s48, v155
	s_add_u32 s100, s26, s10
	s_addc_u32 s101, s27, s11
	s_mov_b32 m0, s49
	ds_read_b128 v[216:219], v166
	ds_read_b128 v[220:223], v166 offset:1024
	ds_read_b128 v[224:227], v166 offset:2048
	ds_read_b128 v[228:231], v166 offset:3072
	global_load_lds_dwordx4 v0, s[100:101]
	s_add_u32 s100, s26, s10
	s_addc_u32 s101, s27, s11
	s_add_i32 m0, s49, 0x2000
	s_nop 0
	global_load_lds_dwordx4 v138, s[100:101]
	s_barrier
	s_waitcnt lgkmcnt(0)
	s_setprio 1
	s_waitcnt lgkmcnt(0)
	v_mfma_f32_16x16x32_bf16 v[118:121], v[216:219], v[184:187], v[118:121]
	v_mfma_f32_16x16x32_bf16 v[114:117], v[224:227], v[184:187], v[114:117]
	v_mfma_f32_16x16x32_bf16 v[102:105], v[216:219], v[192:195], v[102:105]
	v_mfma_f32_16x16x32_bf16 v[98:101], v[224:227], v[192:195], v[98:101]
	v_mfma_f32_16x16x32_bf16 v[86:89], v[216:219], v[200:203], v[86:89]
	v_mfma_f32_16x16x32_bf16 v[82:85], v[224:227], v[200:203], v[82:85]
	v_mfma_f32_16x16x32_bf16 v[70:73], v[216:219], v[208:211], v[70:73]
	v_mfma_f32_16x16x32_bf16 v[66:69], v[224:227], v[208:211], v[66:69]
	v_mfma_f32_16x16x32_bf16 v[118:121], v[220:223], v[188:191], v[118:121]
	v_mfma_f32_16x16x32_bf16 v[114:117], v[228:231], v[188:191], v[114:117]
	v_mfma_f32_16x16x32_bf16 v[102:105], v[220:223], v[196:199], v[102:105]
	v_mfma_f32_16x16x32_bf16 v[98:101], v[228:231], v[196:199], v[98:101]
	v_mfma_f32_16x16x32_bf16 v[86:89], v[220:223], v[204:207], v[86:89]
	v_mfma_f32_16x16x32_bf16 v[82:85], v[228:231], v[204:207], v[82:85]
	v_mfma_f32_16x16x32_bf16 v[70:73], v[220:223], v[212:215], v[70:73]
	v_mfma_f32_16x16x32_bf16 v[66:69], v[228:231], v[212:215], v[66:69]
	s_setprio 0
	s_mov_b32 m0, s52
	s_barrier
	ds_read_b128 v[184:187], v157 offset:49152
	ds_read_b128 v[188:191], v157 offset:50176
	ds_read_b128 v[192:195], v157 offset:51200
	ds_read_b128 v[196:199], v157 offset:52224
	ds_read_b128 v[200:203], v157 offset:53248
	ds_read_b128 v[204:207], v157 offset:54272
	ds_read_b128 v[208:211], v157 offset:55296
	ds_read_b128 v[212:215], v157 offset:56320
	global_load_lds_dwordx4 v142, s[42:43]
	s_mov_b32 m0, s53
	s_nop 0
	global_load_lds_dwordx4 v140, s[42:43]
	s_barrier
	s_waitcnt lgkmcnt(0)
	s_setprio 1
	s_waitcnt lgkmcnt(0)
	v_mfma_f32_16x16x32_bf16 v[62:65], v[148:151], v[184:187], v[62:65]
	v_mfma_f32_16x16x32_bf16 v[58:61], v[162:165], v[184:187], v[58:61]
	v_mfma_f32_16x16x32_bf16 v[46:49], v[148:151], v[192:195], v[46:49]
	v_mfma_f32_16x16x32_bf16 v[42:45], v[162:165], v[192:195], v[42:45]
	v_mfma_f32_16x16x32_bf16 v[30:33], v[148:151], v[200:203], v[30:33]
	v_mfma_f32_16x16x32_bf16 v[26:29], v[162:165], v[200:203], v[26:29]
	v_mfma_f32_16x16x32_bf16 v[14:17], v[148:151], v[208:211], v[14:17]
	v_mfma_f32_16x16x32_bf16 v[10:13], v[162:165], v[208:211], v[10:13]
	v_mfma_f32_16x16x32_bf16 v[62:65], v[158:161], v[188:191], v[62:65]
	v_mfma_f32_16x16x32_bf16 v[58:61], v[180:183], v[188:191], v[58:61]
	v_mfma_f32_16x16x32_bf16 v[46:49], v[158:161], v[196:199], v[46:49]
	v_mfma_f32_16x16x32_bf16 v[42:45], v[180:183], v[196:199], v[42:45]
	v_mfma_f32_16x16x32_bf16 v[30:33], v[158:161], v[204:207], v[30:33]
	v_mfma_f32_16x16x32_bf16 v[26:29], v[180:183], v[204:207], v[26:29]
	v_mfma_f32_16x16x32_bf16 v[14:17], v[158:161], v[212:215], v[14:17]
	v_mfma_f32_16x16x32_bf16 v[10:13], v[180:183], v[212:215], v[10:13]
	s_setprio 0
	s_barrier
	s_add_u32 s26, s26, 0x160080
	s_addc_u32 s27, s27, 0
	s_add_i32 s42, s48, s6
	s_mov_b32 m0, s42
	s_nop 0
	global_load_lds_dwordx4 v0, s[26:27]
	s_add_i32 m0, s42, 0x2000
	s_nop 0
	global_load_lds_dwordx4 v138, s[26:27]
	s_waitcnt vmcnt(6)
	s_barrier
	s_setprio 1
	v_mfma_f32_16x16x32_bf16 v[54:57], v[216:219], v[184:187], v[54:57]
	v_mfma_f32_16x16x32_bf16 v[50:53], v[224:227], v[184:187], v[50:53]
	v_mfma_f32_16x16x32_bf16 v[38:41], v[216:219], v[192:195], v[38:41]
	v_mfma_f32_16x16x32_bf16 v[34:37], v[224:227], v[192:195], v[34:37]
	v_mfma_f32_16x16x32_bf16 v[22:25], v[216:219], v[200:203], v[22:25]
	v_mfma_f32_16x16x32_bf16 v[18:21], v[224:227], v[200:203], v[18:21]
	v_mfma_f32_16x16x32_bf16 v[6:9], v[216:219], v[208:211], v[6:9]
	v_mfma_f32_16x16x32_bf16 v[2:5], v[224:227], v[208:211], v[2:5]
	v_mfma_f32_16x16x32_bf16 v[54:57], v[220:223], v[188:191], v[54:57]
	v_mfma_f32_16x16x32_bf16 v[50:53], v[228:231], v[188:191], v[50:53]
	v_mfma_f32_16x16x32_bf16 v[38:41], v[220:223], v[196:199], v[38:41]
	v_mfma_f32_16x16x32_bf16 v[34:37], v[228:231], v[196:199], v[34:37]
	v_mfma_f32_16x16x32_bf16 v[22:25], v[220:223], v[204:207], v[22:25]
	v_mfma_f32_16x16x32_bf16 v[18:21], v[228:231], v[204:207], v[18:21]
	v_mfma_f32_16x16x32_bf16 v[6:9], v[220:223], v[212:215], v[6:9]
	v_mfma_f32_16x16x32_bf16 v[2:5], v[228:231], v[212:215], v[2:5]
	s_setprio 0
	s_add_i32 s61, s61, 2
	s_add_u32 s59, s59, 0x100
	s_addc_u32 s60, s60, 0
	s_add_u32 s38, s38, 0x10000
	s_addc_u32 s39, s39, 0
	s_cmpk_gt_u32 s61, 0x55
	s_barrier
	s_cbranch_scc0 .LBB0_182
	v_lshl_add_u32 v152, s58, 8, v154
	v_lshl_or_b32 v150, s57, 8, v156
	v_ashrrev_i32_e32 v153, 31, v152
	v_ashrrev_i32_e32 v151, 31, v150
	v_lshlrev_b64 v[134:135], 11, v[152:153]
	v_lshl_add_u64 v[134:135], v[134:135], 0, v[150:151]
	v_lshlrev_b64 v[148:149], 2, v[134:135]
	v_lshl_add_u64 v[134:135], s[22:23], 0, v[148:149]
	v_lshl_add_u64 v[158:159], s[76:77], 0, v[148:149]
	v_readlane_b32 s62, v254, 34
	v_readlane_b32 s64, v254, 36
	v_readlane_b32 s60, v254, 39
	s_and_b64 vcc, exec, s[40:41]
	s_mov_b32 s57, s55
	s_mov_b32 s58, s56
	s_mov_b64 s[38:39], s[0:1]
	v_readlane_b32 s63, v254, 35
	v_readlane_b32 s65, v254, 37
	v_readlane_b32 s61, v254, 40
	v_mov_b64_e32 v[162:163], v[134:135]
	v_mov_b64_e32 v[152:153], v[158:159]
	global_load_dwordx4 v[180:183], v[162:163], off
	global_load_dwordx4 v[184:187], v[162:163], off offset:16
	global_load_dwordx4 v[188:191], v[162:163], off offset:512
	global_load_dwordx4 v[192:195], v[162:163], off offset:528
	s_mov_b64 s[26:27], 0x20000
	v_lshl_add_u64 v[164:165], v[134:135], 0, s[26:27]
	v_lshl_add_u64 v[160:161], v[158:159], 0, s[26:27]
	global_load_dwordx4 v[196:199], v[164:165], off
	global_load_dwordx4 v[200:203], v[164:165], off offset:16
	global_load_dwordx4 v[204:207], v[164:165], off offset:512
	global_load_dwordx4 v[208:211], v[164:165], off offset:528
	s_mov_b64 s[26:27], 0x40000
	v_lshl_add_u64 v[150:151], v[134:135], 0, s[26:27]
	v_lshl_add_u64 v[148:149], v[158:159], 0, s[26:27]
	global_load_dwordx4 v[212:215], v[150:151], off
	global_load_dwordx4 v[216:219], v[150:151], off offset:16
	global_load_dwordx4 v[220:223], v[150:151], off offset:512
	global_load_dwordx4 v[224:227], v[150:151], off offset:528
	s_waitcnt vmcnt(8)
	v_pk_fma_f32 v[126:127], v[126:127], 0.5, v[180:181] op_sel_hi:[1,0,1]
	v_pk_fma_f32 v[128:129], v[128:129], 0.5, v[182:183] op_sel_hi:[1,0,1]
	v_pk_fma_f32 v[122:123], v[122:123], 0.5, v[184:185] op_sel_hi:[1,0,1]
	v_pk_fma_f32 v[124:125], v[124:125], 0.5, v[186:187] op_sel_hi:[1,0,1]
	v_pk_fma_f32 v[118:119], v[118:119], 0.5, v[188:189] op_sel_hi:[1,0,1]
	v_pk_fma_f32 v[120:121], v[120:121], 0.5, v[190:191] op_sel_hi:[1,0,1]
	v_pk_fma_f32 v[114:115], v[114:115], 0.5, v[192:193] op_sel_hi:[1,0,1]
	v_pk_fma_f32 v[116:117], v[116:117], 0.5, v[194:195] op_sel_hi:[1,0,1]
	global_store_dwordx4 v[152:153], v[126:129], off
	global_store_dwordx4 v[152:153], v[122:125], off offset:16
	global_store_dwordx4 v[152:153], v[118:121], off offset:512
	global_store_dwordx4 v[152:153], v[114:117], off offset:528
	s_mov_b64 s[26:27], 0x60000
	v_lshl_add_u64 v[228:229], v[134:135], 0, s[26:27]
	v_lshl_add_u64 v[230:231], v[158:159], 0, s[26:27]
	global_load_dwordx4 v[180:183], v[228:229], off
	global_load_dwordx4 v[184:187], v[228:229], off offset:16
	global_load_dwordx4 v[188:191], v[228:229], off offset:512
	global_load_dwordx4 v[192:195], v[228:229], off offset:528
	s_waitcnt vmcnt(12)
	v_pk_fma_f32 v[110:111], v[110:111], 0.5, v[196:197] op_sel_hi:[1,0,1]
	v_pk_fma_f32 v[112:113], v[112:113], 0.5, v[198:199] op_sel_hi:[1,0,1]
	v_pk_fma_f32 v[106:107], v[106:107], 0.5, v[200:201] op_sel_hi:[1,0,1]
	v_pk_fma_f32 v[108:109], v[108:109], 0.5, v[202:203] op_sel_hi:[1,0,1]
	v_pk_fma_f32 v[102:103], v[102:103], 0.5, v[204:205] op_sel_hi:[1,0,1]
	v_pk_fma_f32 v[104:105], v[104:105], 0.5, v[206:207] op_sel_hi:[1,0,1]
	v_pk_fma_f32 v[98:99], v[98:99], 0.5, v[208:209] op_sel_hi:[1,0,1]
	v_pk_fma_f32 v[100:101], v[100:101], 0.5, v[210:211] op_sel_hi:[1,0,1]
	global_store_dwordx4 v[160:161], v[110:113], off
	global_store_dwordx4 v[160:161], v[106:109], off offset:16
	global_store_dwordx4 v[160:161], v[102:105], off offset:512
	global_store_dwordx4 v[160:161], v[98:101], off offset:528
	s_mov_b64 s[26:27], 0x100000
	v_lshl_add_u64 v[162:163], v[134:135], 0, s[26:27]
	v_lshl_add_u64 v[152:153], v[158:159], 0, s[26:27]
	global_load_dwordx4 v[196:199], v[162:163], off
	global_load_dwordx4 v[200:203], v[162:163], off offset:16
	global_load_dwordx4 v[204:207], v[162:163], off offset:512
	global_load_dwordx4 v[208:211], v[162:163], off offset:528
	s_waitcnt vmcnt(16)
	v_pk_fma_f32 v[94:95], v[94:95], 0.5, v[212:213] op_sel_hi:[1,0,1]
	v_pk_fma_f32 v[96:97], v[96:97], 0.5, v[214:215] op_sel_hi:[1,0,1]
	v_pk_fma_f32 v[90:91], v[90:91], 0.5, v[216:217] op_sel_hi:[1,0,1]
	v_pk_fma_f32 v[92:93], v[92:93], 0.5, v[218:219] op_sel_hi:[1,0,1]
	v_pk_fma_f32 v[86:87], v[86:87], 0.5, v[220:221] op_sel_hi:[1,0,1]
	v_pk_fma_f32 v[88:89], v[88:89], 0.5, v[222:223] op_sel_hi:[1,0,1]
	v_pk_fma_f32 v[82:83], v[82:83], 0.5, v[224:225] op_sel_hi:[1,0,1]
	v_pk_fma_f32 v[84:85], v[84:85], 0.5, v[226:227] op_sel_hi:[1,0,1]
	global_store_dwordx4 v[148:149], v[94:97], off
	global_store_dwordx4 v[148:149], v[90:93], off offset:16
	global_store_dwordx4 v[148:149], v[86:89], off offset:512
	global_store_dwordx4 v[148:149], v[82:85], off offset:528
	s_mov_b64 s[26:27], 0x120000
	v_lshl_add_u64 v[164:165], v[134:135], 0, s[26:27]
	v_lshl_add_u64 v[160:161], v[158:159], 0, s[26:27]
	global_load_dwordx4 v[212:215], v[164:165], off
	global_load_dwordx4 v[216:219], v[164:165], off offset:16
	global_load_dwordx4 v[220:223], v[164:165], off offset:512
	global_load_dwordx4 v[224:227], v[164:165], off offset:528
	s_waitcnt vmcnt(16)
	v_pk_fma_f32 v[78:79], v[78:79], 0.5, v[180:181] op_sel_hi:[1,0,1]
	v_pk_fma_f32 v[80:81], v[80:81], 0.5, v[182:183] op_sel_hi:[1,0,1]
	v_pk_fma_f32 v[74:75], v[74:75], 0.5, v[184:185] op_sel_hi:[1,0,1]
	v_pk_fma_f32 v[76:77], v[76:77], 0.5, v[186:187] op_sel_hi:[1,0,1]
	v_pk_fma_f32 v[70:71], v[70:71], 0.5, v[188:189] op_sel_hi:[1,0,1]
	v_pk_fma_f32 v[72:73], v[72:73], 0.5, v[190:191] op_sel_hi:[1,0,1]
	v_pk_fma_f32 v[66:67], v[66:67], 0.5, v[192:193] op_sel_hi:[1,0,1]
	v_pk_fma_f32 v[68:69], v[68:69], 0.5, v[194:195] op_sel_hi:[1,0,1]
	global_store_dwordx4 v[230:231], v[78:81], off
	global_store_dwordx4 v[230:231], v[74:77], off offset:16
	global_store_dwordx4 v[230:231], v[70:73], off offset:512
	global_store_dwordx4 v[230:231], v[66:69], off offset:528
	s_mov_b64 s[26:27], 0x140000
	v_lshl_add_u64 v[150:151], v[134:135], 0, s[26:27]
	v_lshl_add_u64 v[148:149], v[158:159], 0, s[26:27]
	global_load_dwordx4 v[180:183], v[150:151], off
	global_load_dwordx4 v[184:187], v[150:151], off offset:16
	global_load_dwordx4 v[188:191], v[150:151], off offset:512
	global_load_dwordx4 v[192:195], v[150:151], off offset:528
	s_waitcnt vmcnt(16)
	v_pk_fma_f32 v[62:63], v[62:63], 0.5, v[196:197] op_sel_hi:[1,0,1]
	v_pk_fma_f32 v[64:65], v[64:65], 0.5, v[198:199] op_sel_hi:[1,0,1]
	v_pk_fma_f32 v[58:59], v[58:59], 0.5, v[200:201] op_sel_hi:[1,0,1]
	v_pk_fma_f32 v[60:61], v[60:61], 0.5, v[202:203] op_sel_hi:[1,0,1]
	v_pk_fma_f32 v[54:55], v[54:55], 0.5, v[204:205] op_sel_hi:[1,0,1]
	v_pk_fma_f32 v[56:57], v[56:57], 0.5, v[206:207] op_sel_hi:[1,0,1]
	v_pk_fma_f32 v[50:51], v[50:51], 0.5, v[208:209] op_sel_hi:[1,0,1]
	v_pk_fma_f32 v[52:53], v[52:53], 0.5, v[210:211] op_sel_hi:[1,0,1]
	global_store_dwordx4 v[152:153], v[62:65], off
	global_store_dwordx4 v[152:153], v[58:61], off offset:16
	global_store_dwordx4 v[152:153], v[54:57], off offset:512
	global_store_dwordx4 v[152:153], v[50:53], off offset:528
	s_mov_b64 s[26:27], 0x160000
	v_lshl_add_u64 v[228:229], v[134:135], 0, s[26:27]
	v_lshl_add_u64 v[230:231], v[158:159], 0, s[26:27]
	global_load_dwordx4 v[196:199], v[228:229], off
	global_load_dwordx4 v[200:203], v[228:229], off offset:16
	global_load_dwordx4 v[204:207], v[228:229], off offset:512
	global_load_dwordx4 v[208:211], v[228:229], off offset:528
	s_waitcnt vmcnt(16)
	v_pk_fma_f32 v[46:47], v[46:47], 0.5, v[212:213] op_sel_hi:[1,0,1]
	v_pk_fma_f32 v[48:49], v[48:49], 0.5, v[214:215] op_sel_hi:[1,0,1]
	v_pk_fma_f32 v[42:43], v[42:43], 0.5, v[216:217] op_sel_hi:[1,0,1]
	v_pk_fma_f32 v[44:45], v[44:45], 0.5, v[218:219] op_sel_hi:[1,0,1]
	v_pk_fma_f32 v[38:39], v[38:39], 0.5, v[220:221] op_sel_hi:[1,0,1]
	v_pk_fma_f32 v[40:41], v[40:41], 0.5, v[222:223] op_sel_hi:[1,0,1]
	v_pk_fma_f32 v[34:35], v[34:35], 0.5, v[224:225] op_sel_hi:[1,0,1]
	v_pk_fma_f32 v[36:37], v[36:37], 0.5, v[226:227] op_sel_hi:[1,0,1]
	global_store_dwordx4 v[160:161], v[46:49], off
	global_store_dwordx4 v[160:161], v[42:45], off offset:16
	global_store_dwordx4 v[160:161], v[38:41], off offset:512
	global_store_dwordx4 v[160:161], v[34:37], off offset:528
	s_waitcnt vmcnt(12)
	v_pk_fma_f32 v[30:31], v[30:31], 0.5, v[180:181] op_sel_hi:[1,0,1]
	v_pk_fma_f32 v[32:33], v[32:33], 0.5, v[182:183] op_sel_hi:[1,0,1]
	v_pk_fma_f32 v[26:27], v[26:27], 0.5, v[184:185] op_sel_hi:[1,0,1]
	v_pk_fma_f32 v[28:29], v[28:29], 0.5, v[186:187] op_sel_hi:[1,0,1]
	v_pk_fma_f32 v[22:23], v[22:23], 0.5, v[188:189] op_sel_hi:[1,0,1]
	v_pk_fma_f32 v[24:25], v[24:25], 0.5, v[190:191] op_sel_hi:[1,0,1]
	v_pk_fma_f32 v[18:19], v[18:19], 0.5, v[192:193] op_sel_hi:[1,0,1]
	v_pk_fma_f32 v[20:21], v[20:21], 0.5, v[194:195] op_sel_hi:[1,0,1]
	global_store_dwordx4 v[148:149], v[30:33], off
	global_store_dwordx4 v[148:149], v[26:29], off offset:16
	global_store_dwordx4 v[148:149], v[22:25], off offset:512
	global_store_dwordx4 v[148:149], v[18:21], off offset:528
	s_waitcnt vmcnt(8)
	v_pk_fma_f32 v[14:15], v[14:15], 0.5, v[196:197] op_sel_hi:[1,0,1]
	v_pk_fma_f32 v[16:17], v[16:17], 0.5, v[198:199] op_sel_hi:[1,0,1]
	v_pk_fma_f32 v[10:11], v[10:11], 0.5, v[200:201] op_sel_hi:[1,0,1]
	v_pk_fma_f32 v[12:13], v[12:13], 0.5, v[202:203] op_sel_hi:[1,0,1]
	v_pk_fma_f32 v[6:7], v[6:7], 0.5, v[204:205] op_sel_hi:[1,0,1]
	v_pk_fma_f32 v[8:9], v[8:9], 0.5, v[206:207] op_sel_hi:[1,0,1]
	v_pk_fma_f32 v[2:3], v[2:3], 0.5, v[208:209] op_sel_hi:[1,0,1]
	v_pk_fma_f32 v[4:5], v[4:5], 0.5, v[210:211] op_sel_hi:[1,0,1]
	global_store_dwordx4 v[230:231], v[14:17], off
	global_store_dwordx4 v[230:231], v[10:13], off offset:16
	global_store_dwordx4 v[230:231], v[6:9], off offset:512
	global_store_dwordx4 v[230:231], v[2:5], off offset:528
	s_mov_b64 s[26:27], s[24:25]
	s_cbranch_vccz .LBB0_171
	s_waitcnt vmcnt(0)
	v_readlane_b32 s52, v254, 26
	v_readlane_b32 s56, v254, 30
	v_readlane_b32 s54, v254, 32
	s_cmpk_gt_u32 s4, 0xff
	v_readlane_b32 s53, v254, 27
	v_readlane_b32 s57, v254, 31
	v_readlane_b32 s55, v254, 33
	s_mov_b64 s[58:59], s[84:85]
	s_cbranch_scc1 .LBB0_186
	s_barrier

.LBB0_360:
	s_add_u32 s26, s42, 0xfff80080
	s_addc_u32 s27, s43, -1
	s_add_i32 s58, 0, 0x10000
	v_add_u32_e32 v134, s58, v153
	ds_read_b128 v[148:151], v134
	ds_read_b128 v[156:159], v134 offset:1024
	ds_read_b128 v[160:163], v134 offset:2048
	ds_read_b128 v[164:167], v134 offset:3072
	s_cmp_eq_u32 s57, 28
	s_cselect_b32 s45, s23, s27
	s_cselect_b32 s44, s53, s26
	s_cselect_b32 s27, s1, s56
	s_cselect_b32 s26, s54, s55
	s_add_i32 m0, s7, 0xc000
	ds_read_b128 v[180:183], v155
	ds_read_b128 v[184:187], v155 offset:1024
	ds_read_b128 v[188:191], v155 offset:2048
	ds_read_b128 v[192:195], v155 offset:3072
	ds_read_b128 v[196:199], v155 offset:4096
	ds_read_b128 v[200:203], v155 offset:5120
	ds_read_b128 v[204:207], v155 offset:6144
	ds_read_b128 v[208:211], v155 offset:7168
	global_load_lds_dwordx4 v144, s[42:43]
	s_add_i32 m0, s7, 0xe000
	s_nop 0
	global_load_lds_dwordx4 v146, s[42:43]
	s_waitcnt lgkmcnt(8)
	s_barrier
	s_waitcnt lgkmcnt(0)
	s_setprio 1
	s_waitcnt lgkmcnt(0)
	v_mfma_f32_16x16x32_bf16 v[126:129], v[148:151], v[180:183], v[126:129]
	v_mfma_f32_16x16x32_bf16 v[122:125], v[160:163], v[180:183], v[122:125]
	v_mfma_f32_16x16x32_bf16 v[118:121], v[148:151], v[188:191], v[118:121]
	v_mfma_f32_16x16x32_bf16 v[110:113], v[160:163], v[188:191], v[110:113]
	v_mfma_f32_16x16x32_bf16 v[102:105], v[148:151], v[196:199], v[102:105]
	v_mfma_f32_16x16x32_bf16 v[94:97], v[160:163], v[196:199], v[94:97]
	v_mfma_f32_16x16x32_bf16 v[86:89], v[148:151], v[204:207], v[86:89]
	v_mfma_f32_16x16x32_bf16 v[78:81], v[160:163], v[204:207], v[78:81]
	v_mfma_f32_16x16x32_bf16 v[126:129], v[156:159], v[184:187], v[126:129]
	v_mfma_f32_16x16x32_bf16 v[122:125], v[164:167], v[184:187], v[122:125]
	v_mfma_f32_16x16x32_bf16 v[118:121], v[156:159], v[192:195], v[118:121]
	v_mfma_f32_16x16x32_bf16 v[110:113], v[164:167], v[192:195], v[110:113]
	v_mfma_f32_16x16x32_bf16 v[102:105], v[156:159], v[200:203], v[102:105]
	v_mfma_f32_16x16x32_bf16 v[94:97], v[164:167], v[200:203], v[94:97]
	v_mfma_f32_16x16x32_bf16 v[86:89], v[156:159], v[208:211], v[86:89]
	v_mfma_f32_16x16x32_bf16 v[78:81], v[164:167], v[208:211], v[78:81]
	s_setprio 0
	s_barrier
	s_add_i32 s60, 0, 0x14000
	v_add_u32_e32 v134, s60, v153
	s_add_i32 s58, s58, s6
	ds_read_b128 v[212:215], v134
	ds_read_b128 v[216:219], v134 offset:1024
	ds_read_b128 v[220:223], v134 offset:2048
	ds_read_b128 v[224:227], v134 offset:3072
	s_mov_b32 m0, s58
	global_load_lds_dwordx4 v0, s[26:27]
	s_add_i32 m0, s58, 0x2000
	s_nop 0
	global_load_lds_dwordx4 v138, s[26:27]
	s_barrier
	s_waitcnt lgkmcnt(0)
	s_setprio 1
	s_waitcnt lgkmcnt(0)
	v_mfma_f32_16x16x32_bf16 v[114:117], v[212:215], v[180:183], v[114:117]
	v_mfma_f32_16x16x32_bf16 v[106:109], v[220:223], v[180:183], v[106:109]
	v_mfma_f32_16x16x32_bf16 v[98:101], v[212:215], v[188:191], v[98:101]
	v_mfma_f32_16x16x32_bf16 v[90:93], v[220:223], v[188:191], v[90:93]
	v_mfma_f32_16x16x32_bf16 v[82:85], v[212:215], v[196:199], v[82:85]
	v_mfma_f32_16x16x32_bf16 v[74:77], v[220:223], v[196:199], v[74:77]
	v_mfma_f32_16x16x32_bf16 v[70:73], v[212:215], v[204:207], v[70:73]
	v_mfma_f32_16x16x32_bf16 v[66:69], v[220:223], v[204:207], v[66:69]
	v_mfma_f32_16x16x32_bf16 v[114:117], v[216:219], v[184:187], v[114:117]
	v_mfma_f32_16x16x32_bf16 v[106:109], v[224:227], v[184:187], v[106:109]
	v_mfma_f32_16x16x32_bf16 v[98:101], v[216:219], v[192:195], v[98:101]
	v_mfma_f32_16x16x32_bf16 v[90:93], v[224:227], v[192:195], v[90:93]
	v_mfma_f32_16x16x32_bf16 v[82:85], v[216:219], v[200:203], v[82:85]
	v_mfma_f32_16x16x32_bf16 v[74:77], v[224:227], v[200:203], v[74:77]
	v_mfma_f32_16x16x32_bf16 v[70:73], v[216:219], v[208:211], v[70:73]
	v_mfma_f32_16x16x32_bf16 v[66:69], v[224:227], v[208:211], v[66:69]
	s_setprio 0
	s_mov_b32 m0, s7
	s_add_u32 vcc_lo, s44, s10
	s_addc_u32 vcc_hi, s45, s11
	s_barrier
	ds_read_b128 v[180:183], v155 offset:16384
	ds_read_b128 v[184:187], v155 offset:17408
	ds_read_b128 v[188:191], v155 offset:18432
	ds_read_b128 v[192:195], v155 offset:19456
	ds_read_b128 v[196:199], v155 offset:20480
	ds_read_b128 v[200:203], v155 offset:21504
	ds_read_b128 v[204:207], v155 offset:22528
	ds_read_b128 v[208:211], v155 offset:23552
	global_load_lds_dwordx4 v142, s[44:45]
	s_mov_b32 m0, s14
	s_nop 0
	global_load_lds_dwordx4 v140, s[44:45]
	s_barrier
	s_waitcnt lgkmcnt(0)
	s_setprio 1
	s_waitcnt lgkmcnt(0)
	v_mfma_f32_16x16x32_bf16 v[62:65], v[148:151], v[180:183], v[62:65]
	v_mfma_f32_16x16x32_bf16 v[58:61], v[160:163], v[180:183], v[58:61]
	v_mfma_f32_16x16x32_bf16 v[54:57], v[148:151], v[188:191], v[54:57]
	v_mfma_f32_16x16x32_bf16 v[46:49], v[160:163], v[188:191], v[46:49]
	v_mfma_f32_16x16x32_bf16 v[38:41], v[148:151], v[196:199], v[38:41]
	v_mfma_f32_16x16x32_bf16 v[30:33], v[160:163], v[196:199], v[30:33]
	v_mfma_f32_16x16x32_bf16 v[22:25], v[148:151], v[204:207], v[22:25]
	v_mfma_f32_16x16x32_bf16 v[14:17], v[160:163], v[204:207], v[14:17]
	v_mfma_f32_16x16x32_bf16 v[62:65], v[156:159], v[184:187], v[62:65]
	v_mfma_f32_16x16x32_bf16 v[58:61], v[164:167], v[184:187], v[58:61]
	v_mfma_f32_16x16x32_bf16 v[54:57], v[156:159], v[192:195], v[54:57]
	v_mfma_f32_16x16x32_bf16 v[46:49], v[164:167], v[192:195], v[46:49]
	v_mfma_f32_16x16x32_bf16 v[38:41], v[156:159], v[200:203], v[38:41]
	v_mfma_f32_16x16x32_bf16 v[30:33], v[164:167], v[200:203], v[30:33]
	v_mfma_f32_16x16x32_bf16 v[22:25], v[156:159], v[208:211], v[22:25]
	v_mfma_f32_16x16x32_bf16 v[14:17], v[164:167], v[208:211], v[14:17]
	s_setprio 0
	s_barrier
	s_add_u32 s58, s26, 0x80000
	s_addc_u32 s59, s27, 0
	s_add_i32 s60, s60, s6
	s_mov_b32 m0, s60
	s_nop 0
	global_load_lds_dwordx4 v0, s[58:59]
	s_add_i32 m0, s60, 0x2000
	s_nop 0
	global_load_lds_dwordx4 v138, s[58:59]
	s_waitcnt vmcnt(6)
	s_barrier
	s_setprio 1
	v_mfma_f32_16x16x32_bf16 v[50:53], v[212:215], v[180:183], v[50:53]
	v_mfma_f32_16x16x32_bf16 v[42:45], v[220:223], v[180:183], v[42:45]
	v_mfma_f32_16x16x32_bf16 v[34:37], v[212:215], v[188:191], v[34:37]
	v_mfma_f32_16x16x32_bf16 v[26:29], v[220:223], v[188:191], v[26:29]
	v_mfma_f32_16x16x32_bf16 v[18:21], v[212:215], v[196:199], v[18:21]
	v_mfma_f32_16x16x32_bf16 v[10:13], v[220:223], v[196:199], v[10:13]
	v_mfma_f32_16x16x32_bf16 v[6:9], v[212:215], v[204:207], v[6:9]
	v_mfma_f32_16x16x32_bf16 v[2:5], v[220:223], v[204:207], v[2:5]
	v_mfma_f32_16x16x32_bf16 v[50:53], v[216:219], v[184:187], v[50:53]
	v_mfma_f32_16x16x32_bf16 v[42:45], v[224:227], v[184:187], v[42:45]
	v_mfma_f32_16x16x32_bf16 v[34:37], v[216:219], v[192:195], v[34:37]
	v_mfma_f32_16x16x32_bf16 v[26:29], v[224:227], v[192:195], v[26:29]
	v_mfma_f32_16x16x32_bf16 v[18:21], v[216:219], v[200:203], v[18:21]
	v_mfma_f32_16x16x32_bf16 v[10:13], v[224:227], v[200:203], v[10:13]
	v_mfma_f32_16x16x32_bf16 v[6:9], v[216:219], v[208:211], v[6:9]
	v_mfma_f32_16x16x32_bf16 v[2:5], v[224:227], v[208:211], v[2:5]
	s_setprio 0
	s_add_i32 s58, 0, 0x18000
	v_add_u32_e32 v164, s58, v153
	s_barrier
	ds_read_b128 v[148:151], v164
	ds_read_b128 v[156:159], v164 offset:1024
	ds_read_b128 v[160:163], v164 offset:2048
	ds_read_b128 v[164:167], v164 offset:3072
	s_add_u32 s44, s44, 0x80000
	s_addc_u32 s45, s45, 0
	s_mov_b32 m0, s46
	ds_read_b128 v[180:183], v155 offset:32768
	ds_read_b128 v[184:187], v155 offset:33792
	ds_read_b128 v[188:191], v155 offset:34816
	ds_read_b128 v[192:195], v155 offset:35840
	ds_read_b128 v[196:199], v155 offset:36864
	ds_read_b128 v[200:203], v155 offset:37888
	ds_read_b128 v[204:207], v155 offset:38912
	ds_read_b128 v[208:211], v155 offset:39936
	global_load_lds_dwordx4 v142, s[44:45]
	s_mov_b32 m0, s47
	s_nop 0
	global_load_lds_dwordx4 v140, s[44:45]
	s_waitcnt lgkmcnt(8)
	s_barrier
	s_waitcnt lgkmcnt(0)
	s_setprio 1
	s_waitcnt lgkmcnt(0)
	v_mfma_f32_16x16x32_bf16 v[126:129], v[148:151], v[180:183], v[126:129]
	v_mfma_f32_16x16x32_bf16 v[122:125], v[160:163], v[180:183], v[122:125]
	v_mfma_f32_16x16x32_bf16 v[118:121], v[148:151], v[188:191], v[118:121]
	v_mfma_f32_16x16x32_bf16 v[110:113], v[160:163], v[188:191], v[110:113]
	v_mfma_f32_16x16x32_bf16 v[102:105], v[148:151], v[196:199], v[102:105]
	v_mfma_f32_16x16x32_bf16 v[94:97], v[160:163], v[196:199], v[94:97]
	v_mfma_f32_16x16x32_bf16 v[86:89], v[148:151], v[204:207], v[86:89]
	v_mfma_f32_16x16x32_bf16 v[78:81], v[160:163], v[204:207], v[78:81]
	v_mfma_f32_16x16x32_bf16 v[126:129], v[156:159], v[184:187], v[126:129]
	v_mfma_f32_16x16x32_bf16 v[122:125], v[164:167], v[184:187], v[122:125]
	v_mfma_f32_16x16x32_bf16 v[118:121], v[156:159], v[192:195], v[118:121]
	v_mfma_f32_16x16x32_bf16 v[110:113], v[164:167], v[192:195], v[110:113]
	v_mfma_f32_16x16x32_bf16 v[102:105], v[156:159], v[200:203], v[102:105]
	v_mfma_f32_16x16x32_bf16 v[94:97], v[164:167], v[200:203], v[94:97]
	v_mfma_f32_16x16x32_bf16 v[86:89], v[156:159], v[208:211], v[86:89]
	v_mfma_f32_16x16x32_bf16 v[78:81], v[164:167], v[208:211], v[78:81]
	s_setprio 0
	s_barrier
	s_add_i32 s44, 0, 0x1c000
	s_add_i32 s45, s58, s6
	v_add_u32_e32 v224, s44, v153
	s_add_u32 s100, s26, s10
	s_addc_u32 s101, s27, s11
	s_mov_b32 m0, s45
	ds_read_b128 v[212:215], v224
	ds_read_b128 v[216:219], v224 offset:1024
	ds_read_b128 v[220:223], v224 offset:2048
	ds_read_b128 v[224:227], v224 offset:3072
	global_load_lds_dwordx4 v0, s[100:101]
	s_add_u32 s100, s26, s10
	s_addc_u32 s101, s27, s11
	s_add_i32 m0, s45, 0x2000
	s_nop 0
	global_load_lds_dwordx4 v138, s[100:101]
	s_barrier
	s_waitcnt lgkmcnt(0)
	s_setprio 1
	s_waitcnt lgkmcnt(0)
	v_mfma_f32_16x16x32_bf16 v[114:117], v[212:215], v[180:183], v[114:117]
	v_mfma_f32_16x16x32_bf16 v[106:109], v[220:223], v[180:183], v[106:109]
	v_mfma_f32_16x16x32_bf16 v[98:101], v[212:215], v[188:191], v[98:101]
	v_mfma_f32_16x16x32_bf16 v[90:93], v[220:223], v[188:191], v[90:93]
	v_mfma_f32_16x16x32_bf16 v[82:85], v[212:215], v[196:199], v[82:85]
	v_mfma_f32_16x16x32_bf16 v[74:77], v[220:223], v[196:199], v[74:77]
	v_mfma_f32_16x16x32_bf16 v[70:73], v[212:215], v[204:207], v[70:73]
	v_mfma_f32_16x16x32_bf16 v[66:69], v[220:223], v[204:207], v[66:69]
	v_mfma_f32_16x16x32_bf16 v[114:117], v[216:219], v[184:187], v[114:117]
	v_mfma_f32_16x16x32_bf16 v[106:109], v[224:227], v[184:187], v[106:109]
	v_mfma_f32_16x16x32_bf16 v[98:101], v[216:219], v[192:195], v[98:101]
	v_mfma_f32_16x16x32_bf16 v[90:93], v[224:227], v[192:195], v[90:93]
	v_mfma_f32_16x16x32_bf16 v[82:85], v[216:219], v[200:203], v[82:85]
	v_mfma_f32_16x16x32_bf16 v[74:77], v[224:227], v[200:203], v[74:77]
	v_mfma_f32_16x16x32_bf16 v[70:73], v[216:219], v[208:211], v[70:73]
	v_mfma_f32_16x16x32_bf16 v[66:69], v[224:227], v[208:211], v[66:69]
	s_setprio 0
	s_mov_b32 m0, s48
	s_barrier
	ds_read_b128 v[180:183], v155 offset:49152
	ds_read_b128 v[184:187], v155 offset:50176
	ds_read_b128 v[188:191], v155 offset:51200
	ds_read_b128 v[192:195], v155 offset:52224
	ds_read_b128 v[196:199], v155 offset:53248
	ds_read_b128 v[200:203], v155 offset:54272
	ds_read_b128 v[204:207], v155 offset:55296
	ds_read_b128 v[208:211], v155 offset:56320
	global_load_lds_dwordx4 v142, vcc
	s_mov_b32 m0, s49
	s_nop 0
	global_load_lds_dwordx4 v140, vcc
	s_barrier
	s_waitcnt lgkmcnt(0)
	s_setprio 1
	s_waitcnt lgkmcnt(0)
	v_mfma_f32_16x16x32_bf16 v[62:65], v[148:151], v[180:183], v[62:65]
	v_mfma_f32_16x16x32_bf16 v[58:61], v[160:163], v[180:183], v[58:61]
	v_mfma_f32_16x16x32_bf16 v[54:57], v[148:151], v[188:191], v[54:57]
	v_mfma_f32_16x16x32_bf16 v[46:49], v[160:163], v[188:191], v[46:49]
	v_mfma_f32_16x16x32_bf16 v[38:41], v[148:151], v[196:199], v[38:41]
	v_mfma_f32_16x16x32_bf16 v[30:33], v[160:163], v[196:199], v[30:33]
	v_mfma_f32_16x16x32_bf16 v[22:25], v[148:151], v[204:207], v[22:25]
	v_mfma_f32_16x16x32_bf16 v[14:17], v[160:163], v[204:207], v[14:17]
	v_mfma_f32_16x16x32_bf16 v[62:65], v[156:159], v[184:187], v[62:65]
	v_mfma_f32_16x16x32_bf16 v[58:61], v[164:167], v[184:187], v[58:61]
	v_mfma_f32_16x16x32_bf16 v[54:57], v[156:159], v[192:195], v[54:57]
	v_mfma_f32_16x16x32_bf16 v[46:49], v[164:167], v[192:195], v[46:49]
	v_mfma_f32_16x16x32_bf16 v[38:41], v[156:159], v[200:203], v[38:41]
	v_mfma_f32_16x16x32_bf16 v[30:33], v[164:167], v[200:203], v[30:33]
	v_mfma_f32_16x16x32_bf16 v[22:25], v[156:159], v[208:211], v[22:25]
	v_mfma_f32_16x16x32_bf16 v[14:17], v[164:167], v[208:211], v[14:17]
	s_setprio 0
	s_barrier
	s_add_u32 s26, s26, 0x80080
	s_addc_u32 s27, s27, 0
	s_add_i32 s44, s44, s6
	s_mov_b32 m0, s44
	s_nop 0
	global_load_lds_dwordx4 v0, s[26:27]
	s_add_i32 m0, s44, 0x2000
	s_nop 0
	global_load_lds_dwordx4 v138, s[26:27]
	s_waitcnt vmcnt(6)
	s_barrier
	s_setprio 1
	v_mfma_f32_16x16x32_bf16 v[50:53], v[212:215], v[180:183], v[50:53]
	v_mfma_f32_16x16x32_bf16 v[42:45], v[220:223], v[180:183], v[42:45]
	v_mfma_f32_16x16x32_bf16 v[34:37], v[212:215], v[188:191], v[34:37]
	v_mfma_f32_16x16x32_bf16 v[26:29], v[220:223], v[188:191], v[26:29]
	v_mfma_f32_16x16x32_bf16 v[18:21], v[212:215], v[196:199], v[18:21]
	v_mfma_f32_16x16x32_bf16 v[10:13], v[220:223], v[196:199], v[10:13]
	v_mfma_f32_16x16x32_bf16 v[6:9], v[212:215], v[204:207], v[6:9]
	v_mfma_f32_16x16x32_bf16 v[2:5], v[220:223], v[204:207], v[2:5]
	v_mfma_f32_16x16x32_bf16 v[50:53], v[216:219], v[184:187], v[50:53]
	v_mfma_f32_16x16x32_bf16 v[42:45], v[224:227], v[184:187], v[42:45]
	v_mfma_f32_16x16x32_bf16 v[34:37], v[216:219], v[192:195], v[34:37]
	v_mfma_f32_16x16x32_bf16 v[26:29], v[224:227], v[192:195], v[26:29]
	v_mfma_f32_16x16x32_bf16 v[18:21], v[216:219], v[200:203], v[18:21]
	v_mfma_f32_16x16x32_bf16 v[10:13], v[224:227], v[200:203], v[10:13]
	v_mfma_f32_16x16x32_bf16 v[6:9], v[216:219], v[208:211], v[6:9]
	v_mfma_f32_16x16x32_bf16 v[2:5], v[224:227], v[208:211], v[2:5]
	s_setprio 0
	s_add_i32 s57, s57, 2
	s_add_u32 s42, s42, 0x100
	s_addc_u32 s43, s43, 0
	s_add_u32 s55, s55, 0x100
	s_addc_u32 s56, s56, 0
	s_cmp_gt_u32 s57, 29
	s_barrier
	s_cbranch_scc0 .LBB0_360
	v_lshl_or_b32 v134, s51, 8, v154
	v_lshl_add_u32 v158, s52, 8, v152
	v_ashrrev_i32_e32 v135, 31, v134
	v_mov_b64_e32 v[148:149], s[88:89]
	v_mad_i64_i32 v[156:157], s[26:27], v158, s35, v[148:149]
	v_lshlrev_b64 v[150:151], 1, v[134:135]
	v_lshl_add_u64 v[134:135], v[156:157], 0, v[150:151]
	v_cvt_pk_bf16_f32 v126, v126, v127
	v_cvt_pk_bf16_f32 v127, v128, v129
	v_cvt_pk_bf16_f32 v128, v122, v123
	v_cvt_pk_bf16_f32 v129, v124, v125
	global_store_dwordx4 v[134:135], v[126:129], off
	v_cvt_pk_bf16_f32 v114, v114, v115
	v_cvt_pk_bf16_f32 v115, v116, v117
	v_cvt_pk_bf16_f32 v116, v106, v107
	v_or_b32_e32 v106, 16, v158
	v_mad_i64_i32 v[106:107], s[26:27], v106, s35, v[148:149]
	v_cvt_pk_bf16_f32 v117, v108, v109
	global_store_dwordx4 v[134:135], v[114:117], off offset:256
	s_and_b64 vcc, exec, s[40:41]
	s_mov_b32 s51, s0
	v_lshl_add_u64 v[114:115], v[106:107], 0, v[150:151]
	v_cvt_pk_bf16_f32 v106, v118, v119
	v_cvt_pk_bf16_f32 v107, v120, v121
	v_cvt_pk_bf16_f32 v108, v110, v111
	v_cvt_pk_bf16_f32 v109, v112, v113
	global_store_dwordx4 v[114:115], v[106:109], off
	v_cvt_pk_bf16_f32 v98, v98, v99
	v_cvt_pk_bf16_f32 v99, v100, v101
	v_cvt_pk_bf16_f32 v100, v90, v91
	v_or_b32_e32 v90, 32, v158
	v_mad_i64_i32 v[90:91], s[26:27], v90, s35, v[148:149]
	v_cvt_pk_bf16_f32 v101, v92, v93
	global_store_dwordx4 v[114:115], v[98:101], off offset:256
	s_mov_b32 s52, s22
	s_mov_b64 s[42:43], s[24:25]
	v_lshl_add_u64 v[98:99], v[90:91], 0, v[150:151]
	v_cvt_pk_bf16_f32 v90, v102, v103
	v_cvt_pk_bf16_f32 v91, v104, v105
	v_cvt_pk_bf16_f32 v92, v94, v95
	v_cvt_pk_bf16_f32 v93, v96, v97
	global_store_dwordx4 v[98:99], v[90:93], off
	v_cvt_pk_bf16_f32 v82, v82, v83
	v_cvt_pk_bf16_f32 v83, v84, v85
	v_cvt_pk_bf16_f32 v84, v74, v75
	v_or_b32_e32 v74, 48, v158
	v_mad_i64_i32 v[74:75], s[26:27], v74, s35, v[148:149]
	v_cvt_pk_bf16_f32 v85, v76, v77
	global_store_dwordx4 v[98:99], v[82:85], off offset:256
	s_nop 1
	v_lshl_add_u64 v[82:83], v[74:75], 0, v[150:151]
	v_cvt_pk_bf16_f32 v74, v86, v87
	v_cvt_pk_bf16_f32 v75, v88, v89
	v_cvt_pk_bf16_f32 v76, v78, v79
	v_cvt_pk_bf16_f32 v77, v80, v81
	global_store_dwordx4 v[82:83], v[74:77], off
	v_cvt_pk_bf16_f32 v70, v70, v71
	v_cvt_pk_bf16_f32 v71, v72, v73
	v_cvt_pk_bf16_f32 v72, v66, v67
	v_add_u32_e32 v66, 0x80, v158
	v_mad_i64_i32 v[66:67], s[26:27], v66, s35, v[148:149]
	v_lshl_add_u64 v[66:67], v[66:67], 0, v[150:151]
	v_cvt_pk_bf16_f32 v73, v68, v69
	global_store_dwordx4 v[82:83], v[70:73], off offset:256
	v_cvt_pk_bf16_f32 v62, v62, v63
	v_cvt_pk_bf16_f32 v63, v64, v65
	v_cvt_pk_bf16_f32 v64, v58, v59
	v_cvt_pk_bf16_f32 v65, v60, v61
	global_store_dwordx4 v[66:67], v[62:65], off
	v_cvt_pk_bf16_f32 v50, v50, v51
	v_cvt_pk_bf16_f32 v51, v52, v53
	v_cvt_pk_bf16_f32 v52, v42, v43
	v_add_u32_e32 v42, 0x90, v158
	v_mad_i64_i32 v[42:43], s[26:27], v42, s35, v[148:149]
	v_cvt_pk_bf16_f32 v53, v44, v45
	global_store_dwordx4 v[66:67], v[50:53], off offset:256
	s_nop 1
	v_lshl_add_u64 v[50:51], v[42:43], 0, v[150:151]
	v_cvt_pk_bf16_f32 v42, v54, v55
	v_cvt_pk_bf16_f32 v43, v56, v57
	v_cvt_pk_bf16_f32 v44, v46, v47
	v_cvt_pk_bf16_f32 v45, v48, v49
	global_store_dwordx4 v[50:51], v[42:45], off
	v_cvt_pk_bf16_f32 v34, v34, v35
	v_cvt_pk_bf16_f32 v35, v36, v37
	v_cvt_pk_bf16_f32 v36, v26, v27
	v_add_u32_e32 v26, 0xa0, v158
	v_mad_i64_i32 v[26:27], s[26:27], v26, s35, v[148:149]
	v_cvt_pk_bf16_f32 v37, v28, v29
	global_store_dwordx4 v[50:51], v[34:37], off offset:256
	s_nop 1
	v_lshl_add_u64 v[34:35], v[26:27], 0, v[150:151]
	v_cvt_pk_bf16_f32 v26, v38, v39
	v_cvt_pk_bf16_f32 v27, v40, v41
	v_cvt_pk_bf16_f32 v28, v30, v31
	v_cvt_pk_bf16_f32 v29, v32, v33
	global_store_dwordx4 v[34:35], v[26:29], off
	v_cvt_pk_bf16_f32 v18, v18, v19
	v_cvt_pk_bf16_f32 v19, v20, v21
	v_cvt_pk_bf16_f32 v20, v10, v11
	v_add_u32_e32 v10, 0xb0, v158
	v_mad_i64_i32 v[10:11], s[26:27], v10, s35, v[148:149]
	v_cvt_pk_bf16_f32 v21, v12, v13
	global_store_dwordx4 v[34:35], v[18:21], off offset:256
	s_mov_b64 s[26:27], s[38:39]
	s_nop 0
	v_lshl_add_u64 v[18:19], v[10:11], 0, v[150:151]
	v_cvt_pk_bf16_f32 v10, v22, v23
	v_cvt_pk_bf16_f32 v11, v24, v25
	v_cvt_pk_bf16_f32 v12, v14, v15
	v_cvt_pk_bf16_f32 v13, v16, v17
	global_store_dwordx4 v[18:19], v[10:13], off
	v_cvt_pk_bf16_f32 v6, v6, v7
	v_cvt_pk_bf16_f32 v7, v8, v9
	v_cvt_pk_bf16_f32 v8, v2, v3
	v_cvt_pk_bf16_f32 v9, v4, v5
	global_store_dwordx4 v[18:19], v[6:9], off offset:256
	s_cbranch_vccz .LBB0_357
	s_waitcnt vmcnt(0)
	v_readlane_b32 s52, v254, 26
	v_readlane_b32 s50, v254, 28
	s_cmpk_gt_u32 s4, 0xff
	v_readlane_b32 s53, v254, 27
	v_readlane_b32 s51, v254, 29
	s_cbranch_scc1 .LBB0_364
	s_barrier

.LBB0_627:
	s_add_u32 s26, s42, 0xfff80080
	s_addc_u32 s27, s43, -1
	s_add_i32 s58, 0, 0x10000
	v_add_u32_e32 v134, s58, v153
	ds_read_b128 v[148:151], v134
	ds_read_b128 v[156:159], v134 offset:1024
	ds_read_b128 v[160:163], v134 offset:2048
	ds_read_b128 v[164:167], v134 offset:3072
	s_cmp_eq_u32 s57, 28
	s_cselect_b32 s45, s23, s27
	s_cselect_b32 s44, s53, s26
	s_cselect_b32 s27, s1, s56
	s_cselect_b32 s26, s54, s55
	s_add_i32 m0, s7, 0xc000
	ds_read_b128 v[180:183], v155
	ds_read_b128 v[184:187], v155 offset:1024
	ds_read_b128 v[188:191], v155 offset:2048
	ds_read_b128 v[192:195], v155 offset:3072
	ds_read_b128 v[196:199], v155 offset:4096
	ds_read_b128 v[200:203], v155 offset:5120
	ds_read_b128 v[204:207], v155 offset:6144
	ds_read_b128 v[208:211], v155 offset:7168
	global_load_lds_dwordx4 v144, s[42:43]
	s_add_i32 m0, s7, 0xe000
	s_nop 0
	global_load_lds_dwordx4 v146, s[42:43]
	s_waitcnt lgkmcnt(8)
	s_barrier
	s_waitcnt lgkmcnt(0)
	s_setprio 1
	s_waitcnt lgkmcnt(0)
	v_mfma_f32_16x16x32_bf16 v[126:129], v[148:151], v[180:183], v[126:129]
	v_mfma_f32_16x16x32_bf16 v[122:125], v[160:163], v[180:183], v[122:125]
	v_mfma_f32_16x16x32_bf16 v[118:121], v[148:151], v[188:191], v[118:121]
	v_mfma_f32_16x16x32_bf16 v[110:113], v[160:163], v[188:191], v[110:113]
	v_mfma_f32_16x16x32_bf16 v[102:105], v[148:151], v[196:199], v[102:105]
	v_mfma_f32_16x16x32_bf16 v[94:97], v[160:163], v[196:199], v[94:97]
	v_mfma_f32_16x16x32_bf16 v[86:89], v[148:151], v[204:207], v[86:89]
	v_mfma_f32_16x16x32_bf16 v[78:81], v[160:163], v[204:207], v[78:81]
	v_mfma_f32_16x16x32_bf16 v[126:129], v[156:159], v[184:187], v[126:129]
	v_mfma_f32_16x16x32_bf16 v[122:125], v[164:167], v[184:187], v[122:125]
	v_mfma_f32_16x16x32_bf16 v[118:121], v[156:159], v[192:195], v[118:121]
	v_mfma_f32_16x16x32_bf16 v[110:113], v[164:167], v[192:195], v[110:113]
	v_mfma_f32_16x16x32_bf16 v[102:105], v[156:159], v[200:203], v[102:105]
	v_mfma_f32_16x16x32_bf16 v[94:97], v[164:167], v[200:203], v[94:97]
	v_mfma_f32_16x16x32_bf16 v[86:89], v[156:159], v[208:211], v[86:89]
	v_mfma_f32_16x16x32_bf16 v[78:81], v[164:167], v[208:211], v[78:81]
	s_setprio 0
	s_barrier
	s_add_i32 s60, 0, 0x14000
	v_add_u32_e32 v134, s60, v153
	s_add_i32 s58, s58, s6
	ds_read_b128 v[212:215], v134
	ds_read_b128 v[216:219], v134 offset:1024
	ds_read_b128 v[220:223], v134 offset:2048
	ds_read_b128 v[224:227], v134 offset:3072
	s_mov_b32 m0, s58
	global_load_lds_dwordx4 v0, s[26:27]
	s_add_i32 m0, s58, 0x2000
	s_nop 0
	global_load_lds_dwordx4 v138, s[26:27]
	s_barrier
	s_waitcnt lgkmcnt(0)
	s_setprio 1
	s_waitcnt lgkmcnt(0)
	v_mfma_f32_16x16x32_bf16 v[114:117], v[212:215], v[180:183], v[114:117]
	v_mfma_f32_16x16x32_bf16 v[106:109], v[220:223], v[180:183], v[106:109]
	v_mfma_f32_16x16x32_bf16 v[98:101], v[212:215], v[188:191], v[98:101]
	v_mfma_f32_16x16x32_bf16 v[90:93], v[220:223], v[188:191], v[90:93]
	v_mfma_f32_16x16x32_bf16 v[82:85], v[212:215], v[196:199], v[82:85]
	v_mfma_f32_16x16x32_bf16 v[74:77], v[220:223], v[196:199], v[74:77]
	v_mfma_f32_16x16x32_bf16 v[70:73], v[212:215], v[204:207], v[70:73]
	v_mfma_f32_16x16x32_bf16 v[66:69], v[220:223], v[204:207], v[66:69]
	v_mfma_f32_16x16x32_bf16 v[114:117], v[216:219], v[184:187], v[114:117]
	v_mfma_f32_16x16x32_bf16 v[106:109], v[224:227], v[184:187], v[106:109]
	v_mfma_f32_16x16x32_bf16 v[98:101], v[216:219], v[192:195], v[98:101]
	v_mfma_f32_16x16x32_bf16 v[90:93], v[224:227], v[192:195], v[90:93]
	v_mfma_f32_16x16x32_bf16 v[82:85], v[216:219], v[200:203], v[82:85]
	v_mfma_f32_16x16x32_bf16 v[74:77], v[224:227], v[200:203], v[74:77]
	v_mfma_f32_16x16x32_bf16 v[70:73], v[216:219], v[208:211], v[70:73]
	v_mfma_f32_16x16x32_bf16 v[66:69], v[224:227], v[208:211], v[66:69]
	s_setprio 0
	s_mov_b32 m0, s7
	s_add_u32 vcc_lo, s44, s10
	s_addc_u32 vcc_hi, s45, s11
	s_barrier
	ds_read_b128 v[180:183], v155 offset:16384
	ds_read_b128 v[184:187], v155 offset:17408
	ds_read_b128 v[188:191], v155 offset:18432
	ds_read_b128 v[192:195], v155 offset:19456
	ds_read_b128 v[196:199], v155 offset:20480
	ds_read_b128 v[200:203], v155 offset:21504
	ds_read_b128 v[204:207], v155 offset:22528
	ds_read_b128 v[208:211], v155 offset:23552
	global_load_lds_dwordx4 v142, s[44:45]
	s_mov_b32 m0, s14
	s_nop 0
	global_load_lds_dwordx4 v140, s[44:45]
	s_barrier
	s_waitcnt lgkmcnt(0)
	s_setprio 1
	s_waitcnt lgkmcnt(0)
	v_mfma_f32_16x16x32_bf16 v[62:65], v[148:151], v[180:183], v[62:65]
	v_mfma_f32_16x16x32_bf16 v[58:61], v[160:163], v[180:183], v[58:61]
	v_mfma_f32_16x16x32_bf16 v[54:57], v[148:151], v[188:191], v[54:57]
	v_mfma_f32_16x16x32_bf16 v[46:49], v[160:163], v[188:191], v[46:49]
	v_mfma_f32_16x16x32_bf16 v[38:41], v[148:151], v[196:199], v[38:41]
	v_mfma_f32_16x16x32_bf16 v[30:33], v[160:163], v[196:199], v[30:33]
	v_mfma_f32_16x16x32_bf16 v[22:25], v[148:151], v[204:207], v[22:25]
	v_mfma_f32_16x16x32_bf16 v[14:17], v[160:163], v[204:207], v[14:17]
	v_mfma_f32_16x16x32_bf16 v[62:65], v[156:159], v[184:187], v[62:65]
	v_mfma_f32_16x16x32_bf16 v[58:61], v[164:167], v[184:187], v[58:61]
	v_mfma_f32_16x16x32_bf16 v[54:57], v[156:159], v[192:195], v[54:57]
	v_mfma_f32_16x16x32_bf16 v[46:49], v[164:167], v[192:195], v[46:49]
	v_mfma_f32_16x16x32_bf16 v[38:41], v[156:159], v[200:203], v[38:41]
	v_mfma_f32_16x16x32_bf16 v[30:33], v[164:167], v[200:203], v[30:33]
	v_mfma_f32_16x16x32_bf16 v[22:25], v[156:159], v[208:211], v[22:25]
	v_mfma_f32_16x16x32_bf16 v[14:17], v[164:167], v[208:211], v[14:17]
	s_setprio 0
	s_barrier
	s_add_u32 s58, s26, 0x80000
	s_addc_u32 s59, s27, 0
	s_add_i32 s60, s60, s6
	s_mov_b32 m0, s60
	s_nop 0
	global_load_lds_dwordx4 v0, s[58:59]
	s_add_i32 m0, s60, 0x2000
	s_nop 0
	global_load_lds_dwordx4 v138, s[58:59]
	s_waitcnt vmcnt(6)
	s_barrier
	s_setprio 1
	v_mfma_f32_16x16x32_bf16 v[50:53], v[212:215], v[180:183], v[50:53]
	v_mfma_f32_16x16x32_bf16 v[42:45], v[220:223], v[180:183], v[42:45]
	v_mfma_f32_16x16x32_bf16 v[34:37], v[212:215], v[188:191], v[34:37]
	v_mfma_f32_16x16x32_bf16 v[26:29], v[220:223], v[188:191], v[26:29]
	v_mfma_f32_16x16x32_bf16 v[18:21], v[212:215], v[196:199], v[18:21]
	v_mfma_f32_16x16x32_bf16 v[10:13], v[220:223], v[196:199], v[10:13]
	v_mfma_f32_16x16x32_bf16 v[6:9], v[212:215], v[204:207], v[6:9]
	v_mfma_f32_16x16x32_bf16 v[2:5], v[220:223], v[204:207], v[2:5]
	v_mfma_f32_16x16x32_bf16 v[50:53], v[216:219], v[184:187], v[50:53]
	v_mfma_f32_16x16x32_bf16 v[42:45], v[224:227], v[184:187], v[42:45]
	v_mfma_f32_16x16x32_bf16 v[34:37], v[216:219], v[192:195], v[34:37]
	v_mfma_f32_16x16x32_bf16 v[26:29], v[224:227], v[192:195], v[26:29]
	v_mfma_f32_16x16x32_bf16 v[18:21], v[216:219], v[200:203], v[18:21]
	v_mfma_f32_16x16x32_bf16 v[10:13], v[224:227], v[200:203], v[10:13]
	v_mfma_f32_16x16x32_bf16 v[6:9], v[216:219], v[208:211], v[6:9]
	v_mfma_f32_16x16x32_bf16 v[2:5], v[224:227], v[208:211], v[2:5]
	s_setprio 0
	s_add_i32 s58, 0, 0x18000
	v_add_u32_e32 v164, s58, v153
	s_barrier
	ds_read_b128 v[148:151], v164
	ds_read_b128 v[156:159], v164 offset:1024
	ds_read_b128 v[160:163], v164 offset:2048
	ds_read_b128 v[164:167], v164 offset:3072
	s_add_u32 s44, s44, 0x80000
	s_addc_u32 s45, s45, 0
	s_mov_b32 m0, s46
	ds_read_b128 v[180:183], v155 offset:32768
	ds_read_b128 v[184:187], v155 offset:33792
	ds_read_b128 v[188:191], v155 offset:34816
	ds_read_b128 v[192:195], v155 offset:35840
	ds_read_b128 v[196:199], v155 offset:36864
	ds_read_b128 v[200:203], v155 offset:37888
	ds_read_b128 v[204:207], v155 offset:38912
	ds_read_b128 v[208:211], v155 offset:39936
	global_load_lds_dwordx4 v142, s[44:45]
	s_mov_b32 m0, s47
	s_nop 0
	global_load_lds_dwordx4 v140, s[44:45]
	s_waitcnt lgkmcnt(8)
	s_barrier
	s_waitcnt lgkmcnt(0)
	s_setprio 1
	s_waitcnt lgkmcnt(0)
	v_mfma_f32_16x16x32_bf16 v[126:129], v[148:151], v[180:183], v[126:129]
	v_mfma_f32_16x16x32_bf16 v[122:125], v[160:163], v[180:183], v[122:125]
	v_mfma_f32_16x16x32_bf16 v[118:121], v[148:151], v[188:191], v[118:121]
	v_mfma_f32_16x16x32_bf16 v[110:113], v[160:163], v[188:191], v[110:113]
	v_mfma_f32_16x16x32_bf16 v[102:105], v[148:151], v[196:199], v[102:105]
	v_mfma_f32_16x16x32_bf16 v[94:97], v[160:163], v[196:199], v[94:97]
	v_mfma_f32_16x16x32_bf16 v[86:89], v[148:151], v[204:207], v[86:89]
	v_mfma_f32_16x16x32_bf16 v[78:81], v[160:163], v[204:207], v[78:81]
	v_mfma_f32_16x16x32_bf16 v[126:129], v[156:159], v[184:187], v[126:129]
	v_mfma_f32_16x16x32_bf16 v[122:125], v[164:167], v[184:187], v[122:125]
	v_mfma_f32_16x16x32_bf16 v[118:121], v[156:159], v[192:195], v[118:121]
	v_mfma_f32_16x16x32_bf16 v[110:113], v[164:167], v[192:195], v[110:113]
	v_mfma_f32_16x16x32_bf16 v[102:105], v[156:159], v[200:203], v[102:105]
	v_mfma_f32_16x16x32_bf16 v[94:97], v[164:167], v[200:203], v[94:97]
	v_mfma_f32_16x16x32_bf16 v[86:89], v[156:159], v[208:211], v[86:89]
	v_mfma_f32_16x16x32_bf16 v[78:81], v[164:167], v[208:211], v[78:81]
	s_setprio 0
	s_barrier
	s_add_i32 s44, 0, 0x1c000
	s_add_i32 s45, s58, s6
	v_add_u32_e32 v224, s44, v153
	s_add_u32 s100, s26, s10
	s_addc_u32 s101, s27, s11
	s_mov_b32 m0, s45
	ds_read_b128 v[212:215], v224
	ds_read_b128 v[216:219], v224 offset:1024
	ds_read_b128 v[220:223], v224 offset:2048
	ds_read_b128 v[224:227], v224 offset:3072
	global_load_lds_dwordx4 v0, s[100:101]
	s_add_u32 s100, s26, s10
	s_addc_u32 s101, s27, s11
	s_add_i32 m0, s45, 0x2000
	s_nop 0
	global_load_lds_dwordx4 v138, s[100:101]
	s_barrier
	s_waitcnt lgkmcnt(0)
	s_setprio 1
	s_waitcnt lgkmcnt(0)
	v_mfma_f32_16x16x32_bf16 v[114:117], v[212:215], v[180:183], v[114:117]
	v_mfma_f32_16x16x32_bf16 v[106:109], v[220:223], v[180:183], v[106:109]
	v_mfma_f32_16x16x32_bf16 v[98:101], v[212:215], v[188:191], v[98:101]
	v_mfma_f32_16x16x32_bf16 v[90:93], v[220:223], v[188:191], v[90:93]
	v_mfma_f32_16x16x32_bf16 v[82:85], v[212:215], v[196:199], v[82:85]
	v_mfma_f32_16x16x32_bf16 v[74:77], v[220:223], v[196:199], v[74:77]
	v_mfma_f32_16x16x32_bf16 v[70:73], v[212:215], v[204:207], v[70:73]
	v_mfma_f32_16x16x32_bf16 v[66:69], v[220:223], v[204:207], v[66:69]
	v_mfma_f32_16x16x32_bf16 v[114:117], v[216:219], v[184:187], v[114:117]
	v_mfma_f32_16x16x32_bf16 v[106:109], v[224:227], v[184:187], v[106:109]
	v_mfma_f32_16x16x32_bf16 v[98:101], v[216:219], v[192:195], v[98:101]
	v_mfma_f32_16x16x32_bf16 v[90:93], v[224:227], v[192:195], v[90:93]
	v_mfma_f32_16x16x32_bf16 v[82:85], v[216:219], v[200:203], v[82:85]
	v_mfma_f32_16x16x32_bf16 v[74:77], v[224:227], v[200:203], v[74:77]
	v_mfma_f32_16x16x32_bf16 v[70:73], v[216:219], v[208:211], v[70:73]
	v_mfma_f32_16x16x32_bf16 v[66:69], v[224:227], v[208:211], v[66:69]
	s_setprio 0
	s_mov_b32 m0, s48
	s_barrier
	ds_read_b128 v[180:183], v155 offset:49152
	ds_read_b128 v[184:187], v155 offset:50176
	ds_read_b128 v[188:191], v155 offset:51200
	ds_read_b128 v[192:195], v155 offset:52224
	ds_read_b128 v[196:199], v155 offset:53248
	ds_read_b128 v[200:203], v155 offset:54272
	ds_read_b128 v[204:207], v155 offset:55296
	ds_read_b128 v[208:211], v155 offset:56320
	global_load_lds_dwordx4 v142, vcc
	s_mov_b32 m0, s49
	s_nop 0
	global_load_lds_dwordx4 v140, vcc
	s_barrier
	s_waitcnt lgkmcnt(0)
	s_setprio 1
	s_waitcnt lgkmcnt(0)
	v_mfma_f32_16x16x32_bf16 v[62:65], v[148:151], v[180:183], v[62:65]
	v_mfma_f32_16x16x32_bf16 v[58:61], v[160:163], v[180:183], v[58:61]
	v_mfma_f32_16x16x32_bf16 v[54:57], v[148:151], v[188:191], v[54:57]
	v_mfma_f32_16x16x32_bf16 v[46:49], v[160:163], v[188:191], v[46:49]
	v_mfma_f32_16x16x32_bf16 v[38:41], v[148:151], v[196:199], v[38:41]
	v_mfma_f32_16x16x32_bf16 v[30:33], v[160:163], v[196:199], v[30:33]
	v_mfma_f32_16x16x32_bf16 v[22:25], v[148:151], v[204:207], v[22:25]
	v_mfma_f32_16x16x32_bf16 v[14:17], v[160:163], v[204:207], v[14:17]
	v_mfma_f32_16x16x32_bf16 v[62:65], v[156:159], v[184:187], v[62:65]
	v_mfma_f32_16x16x32_bf16 v[58:61], v[164:167], v[184:187], v[58:61]
	v_mfma_f32_16x16x32_bf16 v[54:57], v[156:159], v[192:195], v[54:57]
	v_mfma_f32_16x16x32_bf16 v[46:49], v[164:167], v[192:195], v[46:49]
	v_mfma_f32_16x16x32_bf16 v[38:41], v[156:159], v[200:203], v[38:41]
	v_mfma_f32_16x16x32_bf16 v[30:33], v[164:167], v[200:203], v[30:33]
	v_mfma_f32_16x16x32_bf16 v[22:25], v[156:159], v[208:211], v[22:25]
	v_mfma_f32_16x16x32_bf16 v[14:17], v[164:167], v[208:211], v[14:17]
	s_setprio 0
	s_barrier
	s_add_u32 s26, s26, 0x80080
	s_addc_u32 s27, s27, 0
	s_add_i32 s44, s44, s6
	s_mov_b32 m0, s44
	s_nop 0
	global_load_lds_dwordx4 v0, s[26:27]
	s_add_i32 m0, s44, 0x2000
	s_nop 0
	global_load_lds_dwordx4 v138, s[26:27]
	s_waitcnt vmcnt(6)
	s_barrier
	s_setprio 1
	v_mfma_f32_16x16x32_bf16 v[50:53], v[212:215], v[180:183], v[50:53]
	v_mfma_f32_16x16x32_bf16 v[42:45], v[220:223], v[180:183], v[42:45]
	v_mfma_f32_16x16x32_bf16 v[34:37], v[212:215], v[188:191], v[34:37]
	v_mfma_f32_16x16x32_bf16 v[26:29], v[220:223], v[188:191], v[26:29]
	v_mfma_f32_16x16x32_bf16 v[18:21], v[212:215], v[196:199], v[18:21]
	v_mfma_f32_16x16x32_bf16 v[10:13], v[220:223], v[196:199], v[10:13]
	v_mfma_f32_16x16x32_bf16 v[6:9], v[212:215], v[204:207], v[6:9]
	v_mfma_f32_16x16x32_bf16 v[2:5], v[220:223], v[204:207], v[2:5]
	v_mfma_f32_16x16x32_bf16 v[50:53], v[216:219], v[184:187], v[50:53]
	v_mfma_f32_16x16x32_bf16 v[42:45], v[224:227], v[184:187], v[42:45]
	v_mfma_f32_16x16x32_bf16 v[34:37], v[216:219], v[192:195], v[34:37]
	v_mfma_f32_16x16x32_bf16 v[26:29], v[224:227], v[192:195], v[26:29]
	v_mfma_f32_16x16x32_bf16 v[18:21], v[216:219], v[200:203], v[18:21]
	v_mfma_f32_16x16x32_bf16 v[10:13], v[224:227], v[200:203], v[10:13]
	v_mfma_f32_16x16x32_bf16 v[6:9], v[216:219], v[208:211], v[6:9]
	v_mfma_f32_16x16x32_bf16 v[2:5], v[224:227], v[208:211], v[2:5]
	s_setprio 0
	s_add_i32 s57, s57, 2
	s_add_u32 s42, s42, 0x100
	s_addc_u32 s43, s43, 0
	s_add_u32 s55, s55, 0x100
	s_addc_u32 s56, s56, 0
	s_cmp_gt_u32 s57, 29
	s_barrier
	s_cbranch_scc0 .LBB0_627
	v_lshl_or_b32 v134, s51, 8, v154
	v_lshl_add_u32 v158, s52, 8, v152
	v_ashrrev_i32_e32 v135, 31, v134
	v_mov_b64_e32 v[148:149], s[88:89]
	s_movk_i32 s1, 0x2200
	v_mad_i64_i32 v[156:157], s[26:27], v158, s1, v[148:149]
	v_lshlrev_b64 v[150:151], 1, v[134:135]
	v_lshl_add_u64 v[134:135], v[156:157], 0, v[150:151]
	v_cvt_pk_bf16_f32 v126, v126, v127
	v_cvt_pk_bf16_f32 v127, v128, v129
	v_cvt_pk_bf16_f32 v128, v122, v123
	v_cvt_pk_bf16_f32 v129, v124, v125
	global_store_dwordx4 v[134:135], v[126:129], off
	v_cvt_pk_bf16_f32 v114, v114, v115
	v_cvt_pk_bf16_f32 v115, v116, v117
	v_cvt_pk_bf16_f32 v116, v106, v107
	v_or_b32_e32 v106, 16, v158
	v_mad_i64_i32 v[106:107], s[26:27], v106, s1, v[148:149]
	v_cvt_pk_bf16_f32 v117, v108, v109
	global_store_dwordx4 v[134:135], v[114:117], off offset:256
	s_and_b64 vcc, exec, s[40:41]
	s_mov_b32 s51, s0
	v_lshl_add_u64 v[114:115], v[106:107], 0, v[150:151]
	v_cvt_pk_bf16_f32 v106, v118, v119
	v_cvt_pk_bf16_f32 v107, v120, v121
	v_cvt_pk_bf16_f32 v108, v110, v111
	v_cvt_pk_bf16_f32 v109, v112, v113
	global_store_dwordx4 v[114:115], v[106:109], off
	v_cvt_pk_bf16_f32 v98, v98, v99
	v_cvt_pk_bf16_f32 v99, v100, v101
	v_cvt_pk_bf16_f32 v100, v90, v91
	v_or_b32_e32 v90, 32, v158
	v_mad_i64_i32 v[90:91], s[26:27], v90, s1, v[148:149]
	v_cvt_pk_bf16_f32 v101, v92, v93
	global_store_dwordx4 v[114:115], v[98:101], off offset:256
	s_mov_b32 s52, s22
	s_mov_b64 s[42:43], s[24:25]
	v_lshl_add_u64 v[98:99], v[90:91], 0, v[150:151]
	v_cvt_pk_bf16_f32 v90, v102, v103
	v_cvt_pk_bf16_f32 v91, v104, v105
	v_cvt_pk_bf16_f32 v92, v94, v95
	v_cvt_pk_bf16_f32 v93, v96, v97
	global_store_dwordx4 v[98:99], v[90:93], off
	v_cvt_pk_bf16_f32 v82, v82, v83
	v_cvt_pk_bf16_f32 v83, v84, v85
	v_cvt_pk_bf16_f32 v84, v74, v75
	v_or_b32_e32 v74, 48, v158
	v_mad_i64_i32 v[74:75], s[26:27], v74, s1, v[148:149]
	v_cvt_pk_bf16_f32 v85, v76, v77
	global_store_dwordx4 v[98:99], v[82:85], off offset:256
	s_nop 1
	v_lshl_add_u64 v[82:83], v[74:75], 0, v[150:151]
	v_cvt_pk_bf16_f32 v74, v86, v87
	v_cvt_pk_bf16_f32 v75, v88, v89
	v_cvt_pk_bf16_f32 v76, v78, v79
	v_cvt_pk_bf16_f32 v77, v80, v81
	global_store_dwordx4 v[82:83], v[74:77], off
	v_cvt_pk_bf16_f32 v70, v70, v71
	v_cvt_pk_bf16_f32 v71, v72, v73
	v_cvt_pk_bf16_f32 v72, v66, v67
	v_add_u32_e32 v66, 0x80, v158
	v_mad_i64_i32 v[66:67], s[26:27], v66, s1, v[148:149]
	v_lshl_add_u64 v[66:67], v[66:67], 0, v[150:151]
	v_cvt_pk_bf16_f32 v73, v68, v69
	global_store_dwordx4 v[82:83], v[70:73], off offset:256
	v_cvt_pk_bf16_f32 v62, v62, v63
	v_cvt_pk_bf16_f32 v63, v64, v65
	v_cvt_pk_bf16_f32 v64, v58, v59
	v_cvt_pk_bf16_f32 v65, v60, v61
	global_store_dwordx4 v[66:67], v[62:65], off
	v_cvt_pk_bf16_f32 v50, v50, v51
	v_cvt_pk_bf16_f32 v51, v52, v53
	v_cvt_pk_bf16_f32 v52, v42, v43
	v_add_u32_e32 v42, 0x90, v158
	v_mad_i64_i32 v[42:43], s[26:27], v42, s1, v[148:149]
	v_cvt_pk_bf16_f32 v53, v44, v45
	global_store_dwordx4 v[66:67], v[50:53], off offset:256
	s_nop 1
	v_lshl_add_u64 v[50:51], v[42:43], 0, v[150:151]
	v_cvt_pk_bf16_f32 v42, v54, v55
	v_cvt_pk_bf16_f32 v43, v56, v57
	v_cvt_pk_bf16_f32 v44, v46, v47
	v_cvt_pk_bf16_f32 v45, v48, v49
	global_store_dwordx4 v[50:51], v[42:45], off
	v_cvt_pk_bf16_f32 v34, v34, v35
	v_cvt_pk_bf16_f32 v35, v36, v37
	v_cvt_pk_bf16_f32 v36, v26, v27
	v_add_u32_e32 v26, 0xa0, v158
	v_mad_i64_i32 v[26:27], s[26:27], v26, s1, v[148:149]
	v_cvt_pk_bf16_f32 v37, v28, v29
	global_store_dwordx4 v[50:51], v[34:37], off offset:256
	s_nop 1
	v_lshl_add_u64 v[34:35], v[26:27], 0, v[150:151]
	v_cvt_pk_bf16_f32 v26, v38, v39
	v_cvt_pk_bf16_f32 v27, v40, v41
	v_cvt_pk_bf16_f32 v28, v30, v31
	v_cvt_pk_bf16_f32 v29, v32, v33
	global_store_dwordx4 v[34:35], v[26:29], off
	v_cvt_pk_bf16_f32 v18, v18, v19
	v_cvt_pk_bf16_f32 v19, v20, v21
	v_cvt_pk_bf16_f32 v20, v10, v11
	v_add_u32_e32 v10, 0xb0, v158
	v_mad_i64_i32 v[10:11], s[26:27], v10, s1, v[148:149]
	v_cvt_pk_bf16_f32 v21, v12, v13
	global_store_dwordx4 v[34:35], v[18:21], off offset:256
	s_mov_b64 s[26:27], s[38:39]
	s_nop 0
	v_lshl_add_u64 v[18:19], v[10:11], 0, v[150:151]
	v_cvt_pk_bf16_f32 v10, v22, v23
	v_cvt_pk_bf16_f32 v11, v24, v25
	v_cvt_pk_bf16_f32 v12, v14, v15
	v_cvt_pk_bf16_f32 v13, v16, v17
	global_store_dwordx4 v[18:19], v[10:13], off
	v_cvt_pk_bf16_f32 v6, v6, v7
	v_cvt_pk_bf16_f32 v7, v8, v9
	v_cvt_pk_bf16_f32 v8, v2, v3
	v_cvt_pk_bf16_f32 v9, v4, v5
	global_store_dwordx4 v[18:19], v[6:9], off offset:256
	s_cbranch_vccz .LBB0_624
	s_waitcnt vmcnt(0)
	v_readlane_b32 s52, v254, 26
	v_readlane_b32 s50, v254, 28
	s_cmpk_gt_u32 s4, 0xff
	v_readlane_b32 s53, v254, 27
	v_readlane_b32 s51, v254, 29
	s_cbranch_scc1 .LBB0_631
	s_barrier

.LBB0_1034:
	s_add_u32 s26, s42, 0xfff80080
	s_addc_u32 s27, s43, -1
	s_add_i32 s58, 0, 0x10000
	v_add_u32_e32 v134, s58, v155
	ds_read_b128 v[148:151], v134
	ds_read_b128 v[158:161], v134 offset:1024
	ds_read_b128 v[162:165], v134 offset:2048
	ds_read_b128 v[180:183], v134 offset:3072
	s_cmp_eq_u32 s57, 28
	s_cselect_b32 s45, s23, s27
	s_cselect_b32 s44, s53, s26
	s_cselect_b32 s27, s1, s56
	s_cselect_b32 s26, s54, s55
	s_add_i32 m0, s7, 0xc000
	ds_read_b128 v[184:187], v157
	ds_read_b128 v[188:191], v157 offset:1024
	ds_read_b128 v[192:195], v157 offset:2048
	ds_read_b128 v[196:199], v157 offset:3072
	ds_read_b128 v[200:203], v157 offset:4096
	ds_read_b128 v[204:207], v157 offset:5120
	ds_read_b128 v[208:211], v157 offset:6144
	ds_read_b128 v[212:215], v157 offset:7168
	global_load_lds_dwordx4 v144, s[42:43]
	s_add_i32 m0, s7, 0xe000
	s_nop 0
	global_load_lds_dwordx4 v146, s[42:43]
	s_waitcnt lgkmcnt(8)
	s_barrier
	s_waitcnt lgkmcnt(0)
	s_setprio 1
	s_waitcnt lgkmcnt(0)
	v_mfma_f32_16x16x32_bf16 v[126:129], v[148:151], v[184:187], v[126:129]
	v_mfma_f32_16x16x32_bf16 v[122:125], v[162:165], v[184:187], v[122:125]
	v_mfma_f32_16x16x32_bf16 v[110:113], v[148:151], v[192:195], v[110:113]
	v_mfma_f32_16x16x32_bf16 v[106:109], v[162:165], v[192:195], v[106:109]
	v_mfma_f32_16x16x32_bf16 v[94:97], v[148:151], v[200:203], v[94:97]
	v_mfma_f32_16x16x32_bf16 v[90:93], v[162:165], v[200:203], v[90:93]
	v_mfma_f32_16x16x32_bf16 v[78:81], v[148:151], v[208:211], v[78:81]
	v_mfma_f32_16x16x32_bf16 v[74:77], v[162:165], v[208:211], v[74:77]
	v_mfma_f32_16x16x32_bf16 v[126:129], v[158:161], v[188:191], v[126:129]
	v_mfma_f32_16x16x32_bf16 v[122:125], v[180:183], v[188:191], v[122:125]
	v_mfma_f32_16x16x32_bf16 v[110:113], v[158:161], v[196:199], v[110:113]
	v_mfma_f32_16x16x32_bf16 v[106:109], v[180:183], v[196:199], v[106:109]
	v_mfma_f32_16x16x32_bf16 v[94:97], v[158:161], v[204:207], v[94:97]
	v_mfma_f32_16x16x32_bf16 v[90:93], v[180:183], v[204:207], v[90:93]
	v_mfma_f32_16x16x32_bf16 v[78:81], v[158:161], v[212:215], v[78:81]
	v_mfma_f32_16x16x32_bf16 v[74:77], v[180:183], v[212:215], v[74:77]
	s_setprio 0
	s_barrier
	s_add_i32 s60, 0, 0x14000
	v_add_u32_e32 v134, s60, v155
	s_add_i32 s58, s58, s6
	ds_read_b128 v[216:219], v134
	ds_read_b128 v[220:223], v134 offset:1024
	ds_read_b128 v[224:227], v134 offset:2048
	ds_read_b128 v[228:231], v134 offset:3072
	s_mov_b32 m0, s58
	global_load_lds_dwordx4 v0, s[26:27]
	s_add_i32 m0, s58, 0x2000
	s_nop 0
	global_load_lds_dwordx4 v138, s[26:27]
	s_barrier
	s_waitcnt lgkmcnt(0)
	s_setprio 1
	s_waitcnt lgkmcnt(0)
	v_mfma_f32_16x16x32_bf16 v[118:121], v[216:219], v[184:187], v[118:121]
	v_mfma_f32_16x16x32_bf16 v[114:117], v[224:227], v[184:187], v[114:117]
	v_mfma_f32_16x16x32_bf16 v[102:105], v[216:219], v[192:195], v[102:105]
	v_mfma_f32_16x16x32_bf16 v[98:101], v[224:227], v[192:195], v[98:101]
	v_mfma_f32_16x16x32_bf16 v[86:89], v[216:219], v[200:203], v[86:89]
	v_mfma_f32_16x16x32_bf16 v[82:85], v[224:227], v[200:203], v[82:85]
	v_mfma_f32_16x16x32_bf16 v[70:73], v[216:219], v[208:211], v[70:73]
	v_mfma_f32_16x16x32_bf16 v[66:69], v[224:227], v[208:211], v[66:69]
	v_mfma_f32_16x16x32_bf16 v[118:121], v[220:223], v[188:191], v[118:121]
	v_mfma_f32_16x16x32_bf16 v[114:117], v[228:231], v[188:191], v[114:117]
	v_mfma_f32_16x16x32_bf16 v[102:105], v[220:223], v[196:199], v[102:105]
	v_mfma_f32_16x16x32_bf16 v[98:101], v[228:231], v[196:199], v[98:101]
	v_mfma_f32_16x16x32_bf16 v[86:89], v[220:223], v[204:207], v[86:89]
	v_mfma_f32_16x16x32_bf16 v[82:85], v[228:231], v[204:207], v[82:85]
	v_mfma_f32_16x16x32_bf16 v[70:73], v[220:223], v[212:215], v[70:73]
	v_mfma_f32_16x16x32_bf16 v[66:69], v[228:231], v[212:215], v[66:69]
	s_setprio 0
	s_mov_b32 m0, s7
	s_add_u32 vcc_lo, s44, s10
	s_addc_u32 vcc_hi, s45, s11
	s_barrier
	ds_read_b128 v[184:187], v157 offset:16384
	ds_read_b128 v[188:191], v157 offset:17408
	ds_read_b128 v[192:195], v157 offset:18432
	ds_read_b128 v[196:199], v157 offset:19456
	ds_read_b128 v[200:203], v157 offset:20480
	ds_read_b128 v[204:207], v157 offset:21504
	ds_read_b128 v[208:211], v157 offset:22528
	ds_read_b128 v[212:215], v157 offset:23552
	global_load_lds_dwordx4 v142, s[44:45]
	s_mov_b32 m0, s14
	s_nop 0
	global_load_lds_dwordx4 v140, s[44:45]
	s_barrier
	s_waitcnt lgkmcnt(0)
	s_setprio 1
	s_waitcnt lgkmcnt(0)
	v_mfma_f32_16x16x32_bf16 v[62:65], v[148:151], v[184:187], v[62:65]
	v_mfma_f32_16x16x32_bf16 v[58:61], v[162:165], v[184:187], v[58:61]
	v_mfma_f32_16x16x32_bf16 v[46:49], v[148:151], v[192:195], v[46:49]
	v_mfma_f32_16x16x32_bf16 v[42:45], v[162:165], v[192:195], v[42:45]
	v_mfma_f32_16x16x32_bf16 v[30:33], v[148:151], v[200:203], v[30:33]
	v_mfma_f32_16x16x32_bf16 v[26:29], v[162:165], v[200:203], v[26:29]
	v_mfma_f32_16x16x32_bf16 v[14:17], v[148:151], v[208:211], v[14:17]
	v_mfma_f32_16x16x32_bf16 v[10:13], v[162:165], v[208:211], v[10:13]
	v_mfma_f32_16x16x32_bf16 v[62:65], v[158:161], v[188:191], v[62:65]
	v_mfma_f32_16x16x32_bf16 v[58:61], v[180:183], v[188:191], v[58:61]
	v_mfma_f32_16x16x32_bf16 v[46:49], v[158:161], v[196:199], v[46:49]
	v_mfma_f32_16x16x32_bf16 v[42:45], v[180:183], v[196:199], v[42:45]
	v_mfma_f32_16x16x32_bf16 v[30:33], v[158:161], v[204:207], v[30:33]
	v_mfma_f32_16x16x32_bf16 v[26:29], v[180:183], v[204:207], v[26:29]
	v_mfma_f32_16x16x32_bf16 v[14:17], v[158:161], v[212:215], v[14:17]
	v_mfma_f32_16x16x32_bf16 v[10:13], v[180:183], v[212:215], v[10:13]
	s_setprio 0
	s_barrier
	s_add_u32 s58, s26, 0x80000
	s_addc_u32 s59, s27, 0
	s_add_i32 s60, s60, s6
	s_mov_b32 m0, s60
	s_nop 0
	global_load_lds_dwordx4 v0, s[58:59]
	s_add_i32 m0, s60, 0x2000
	s_nop 0
	global_load_lds_dwordx4 v138, s[58:59]
	s_waitcnt vmcnt(6)
	s_barrier
	s_setprio 1
	v_mfma_f32_16x16x32_bf16 v[54:57], v[216:219], v[184:187], v[54:57]
	v_mfma_f32_16x16x32_bf16 v[50:53], v[224:227], v[184:187], v[50:53]
	v_mfma_f32_16x16x32_bf16 v[38:41], v[216:219], v[192:195], v[38:41]
	v_mfma_f32_16x16x32_bf16 v[34:37], v[224:227], v[192:195], v[34:37]
	v_mfma_f32_16x16x32_bf16 v[22:25], v[216:219], v[200:203], v[22:25]
	v_mfma_f32_16x16x32_bf16 v[18:21], v[224:227], v[200:203], v[18:21]
	v_mfma_f32_16x16x32_bf16 v[6:9], v[216:219], v[208:211], v[6:9]
	v_mfma_f32_16x16x32_bf16 v[2:5], v[224:227], v[208:211], v[2:5]
	v_mfma_f32_16x16x32_bf16 v[54:57], v[220:223], v[188:191], v[54:57]
	v_mfma_f32_16x16x32_bf16 v[50:53], v[228:231], v[188:191], v[50:53]
	v_mfma_f32_16x16x32_bf16 v[38:41], v[220:223], v[196:199], v[38:41]
	v_mfma_f32_16x16x32_bf16 v[34:37], v[228:231], v[196:199], v[34:37]
	v_mfma_f32_16x16x32_bf16 v[22:25], v[220:223], v[204:207], v[22:25]
	v_mfma_f32_16x16x32_bf16 v[18:21], v[228:231], v[204:207], v[18:21]
	v_mfma_f32_16x16x32_bf16 v[6:9], v[220:223], v[212:215], v[6:9]
	v_mfma_f32_16x16x32_bf16 v[2:5], v[228:231], v[212:215], v[2:5]
	s_setprio 0
	s_add_i32 s58, 0, 0x18000
	v_add_u32_e32 v180, s58, v155
	s_barrier
	ds_read_b128 v[148:151], v180
	ds_read_b128 v[158:161], v180 offset:1024
	ds_read_b128 v[162:165], v180 offset:2048
	ds_read_b128 v[180:183], v180 offset:3072
	s_add_u32 s44, s44, 0x80000
	s_addc_u32 s45, s45, 0
	s_mov_b32 m0, s46
	ds_read_b128 v[184:187], v157 offset:32768
	ds_read_b128 v[188:191], v157 offset:33792
	ds_read_b128 v[192:195], v157 offset:34816
	ds_read_b128 v[196:199], v157 offset:35840
	ds_read_b128 v[200:203], v157 offset:36864
	ds_read_b128 v[204:207], v157 offset:37888
	ds_read_b128 v[208:211], v157 offset:38912
	ds_read_b128 v[212:215], v157 offset:39936
	global_load_lds_dwordx4 v142, s[44:45]
	s_mov_b32 m0, s47
	s_nop 0
	global_load_lds_dwordx4 v140, s[44:45]
	s_waitcnt lgkmcnt(8)
	s_barrier
	s_waitcnt lgkmcnt(0)
	s_setprio 1
	s_waitcnt lgkmcnt(0)
	v_mfma_f32_16x16x32_bf16 v[126:129], v[148:151], v[184:187], v[126:129]
	v_mfma_f32_16x16x32_bf16 v[122:125], v[162:165], v[184:187], v[122:125]
	v_mfma_f32_16x16x32_bf16 v[110:113], v[148:151], v[192:195], v[110:113]
	v_mfma_f32_16x16x32_bf16 v[106:109], v[162:165], v[192:195], v[106:109]
	v_mfma_f32_16x16x32_bf16 v[94:97], v[148:151], v[200:203], v[94:97]
	v_mfma_f32_16x16x32_bf16 v[90:93], v[162:165], v[200:203], v[90:93]
	v_mfma_f32_16x16x32_bf16 v[78:81], v[148:151], v[208:211], v[78:81]
	v_mfma_f32_16x16x32_bf16 v[74:77], v[162:165], v[208:211], v[74:77]
	v_mfma_f32_16x16x32_bf16 v[126:129], v[158:161], v[188:191], v[126:129]
	v_mfma_f32_16x16x32_bf16 v[122:125], v[180:183], v[188:191], v[122:125]
	v_mfma_f32_16x16x32_bf16 v[110:113], v[158:161], v[196:199], v[110:113]
	v_mfma_f32_16x16x32_bf16 v[106:109], v[180:183], v[196:199], v[106:109]
	v_mfma_f32_16x16x32_bf16 v[94:97], v[158:161], v[204:207], v[94:97]
	v_mfma_f32_16x16x32_bf16 v[90:93], v[180:183], v[204:207], v[90:93]
	v_mfma_f32_16x16x32_bf16 v[78:81], v[158:161], v[212:215], v[78:81]
	v_mfma_f32_16x16x32_bf16 v[74:77], v[180:183], v[212:215], v[74:77]
	s_setprio 0
	s_barrier
	s_add_i32 s44, 0, 0x1c000
	s_add_i32 s45, s58, s6
	v_add_u32_e32 v228, s44, v155
	s_add_u32 s100, s26, s10
	s_addc_u32 s101, s27, s11
	s_mov_b32 m0, s45
	ds_read_b128 v[216:219], v228
	ds_read_b128 v[220:223], v228 offset:1024
	ds_read_b128 v[224:227], v228 offset:2048
	ds_read_b128 v[228:231], v228 offset:3072
	global_load_lds_dwordx4 v0, s[100:101]
	s_add_u32 s100, s26, s10
	s_addc_u32 s101, s27, s11
	s_add_i32 m0, s45, 0x2000
	s_nop 0
	global_load_lds_dwordx4 v138, s[100:101]
	s_barrier
	s_waitcnt lgkmcnt(0)
	s_setprio 1
	s_waitcnt lgkmcnt(0)
	v_mfma_f32_16x16x32_bf16 v[118:121], v[216:219], v[184:187], v[118:121]
	v_mfma_f32_16x16x32_bf16 v[114:117], v[224:227], v[184:187], v[114:117]
	v_mfma_f32_16x16x32_bf16 v[102:105], v[216:219], v[192:195], v[102:105]
	v_mfma_f32_16x16x32_bf16 v[98:101], v[224:227], v[192:195], v[98:101]
	v_mfma_f32_16x16x32_bf16 v[86:89], v[216:219], v[200:203], v[86:89]
	v_mfma_f32_16x16x32_bf16 v[82:85], v[224:227], v[200:203], v[82:85]
	v_mfma_f32_16x16x32_bf16 v[70:73], v[216:219], v[208:211], v[70:73]
	v_mfma_f32_16x16x32_bf16 v[66:69], v[224:227], v[208:211], v[66:69]
	v_mfma_f32_16x16x32_bf16 v[118:121], v[220:223], v[188:191], v[118:121]
	v_mfma_f32_16x16x32_bf16 v[114:117], v[228:231], v[188:191], v[114:117]
	v_mfma_f32_16x16x32_bf16 v[102:105], v[220:223], v[196:199], v[102:105]
	v_mfma_f32_16x16x32_bf16 v[98:101], v[228:231], v[196:199], v[98:101]
	v_mfma_f32_16x16x32_bf16 v[86:89], v[220:223], v[204:207], v[86:89]
	v_mfma_f32_16x16x32_bf16 v[82:85], v[228:231], v[204:207], v[82:85]
	v_mfma_f32_16x16x32_bf16 v[70:73], v[220:223], v[212:215], v[70:73]
	v_mfma_f32_16x16x32_bf16 v[66:69], v[228:231], v[212:215], v[66:69]
	s_setprio 0
	s_mov_b32 m0, s48
	s_barrier
	ds_read_b128 v[184:187], v157 offset:49152
	ds_read_b128 v[188:191], v157 offset:50176
	ds_read_b128 v[192:195], v157 offset:51200
	ds_read_b128 v[196:199], v157 offset:52224
	ds_read_b128 v[200:203], v157 offset:53248
	ds_read_b128 v[204:207], v157 offset:54272
	ds_read_b128 v[208:211], v157 offset:55296
	ds_read_b128 v[212:215], v157 offset:56320
	global_load_lds_dwordx4 v142, vcc
	s_mov_b32 m0, s49
	s_nop 0
	global_load_lds_dwordx4 v140, vcc
	s_barrier
	s_waitcnt lgkmcnt(0)
	s_setprio 1
	s_waitcnt lgkmcnt(0)
	v_mfma_f32_16x16x32_bf16 v[62:65], v[148:151], v[184:187], v[62:65]
	v_mfma_f32_16x16x32_bf16 v[58:61], v[162:165], v[184:187], v[58:61]
	v_mfma_f32_16x16x32_bf16 v[46:49], v[148:151], v[192:195], v[46:49]
	v_mfma_f32_16x16x32_bf16 v[42:45], v[162:165], v[192:195], v[42:45]
	v_mfma_f32_16x16x32_bf16 v[30:33], v[148:151], v[200:203], v[30:33]
	v_mfma_f32_16x16x32_bf16 v[26:29], v[162:165], v[200:203], v[26:29]
	v_mfma_f32_16x16x32_bf16 v[14:17], v[148:151], v[208:211], v[14:17]
	v_mfma_f32_16x16x32_bf16 v[10:13], v[162:165], v[208:211], v[10:13]
	v_mfma_f32_16x16x32_bf16 v[62:65], v[158:161], v[188:191], v[62:65]
	v_mfma_f32_16x16x32_bf16 v[58:61], v[180:183], v[188:191], v[58:61]
	v_mfma_f32_16x16x32_bf16 v[46:49], v[158:161], v[196:199], v[46:49]
	v_mfma_f32_16x16x32_bf16 v[42:45], v[180:183], v[196:199], v[42:45]
	v_mfma_f32_16x16x32_bf16 v[30:33], v[158:161], v[204:207], v[30:33]
	v_mfma_f32_16x16x32_bf16 v[26:29], v[180:183], v[204:207], v[26:29]
	v_mfma_f32_16x16x32_bf16 v[14:17], v[158:161], v[212:215], v[14:17]
	v_mfma_f32_16x16x32_bf16 v[10:13], v[180:183], v[212:215], v[10:13]
	s_setprio 0
	s_barrier
	s_add_u32 s26, s26, 0x80080
	s_addc_u32 s27, s27, 0
	s_add_i32 s44, s44, s6
	s_mov_b32 m0, s44
	s_nop 0
	global_load_lds_dwordx4 v0, s[26:27]
	s_add_i32 m0, s44, 0x2000
	s_nop 0
	global_load_lds_dwordx4 v138, s[26:27]
	s_waitcnt vmcnt(6)
	s_barrier
	s_setprio 1
	v_mfma_f32_16x16x32_bf16 v[54:57], v[216:219], v[184:187], v[54:57]
	v_mfma_f32_16x16x32_bf16 v[50:53], v[224:227], v[184:187], v[50:53]
	v_mfma_f32_16x16x32_bf16 v[38:41], v[216:219], v[192:195], v[38:41]
	v_mfma_f32_16x16x32_bf16 v[34:37], v[224:227], v[192:195], v[34:37]
	v_mfma_f32_16x16x32_bf16 v[22:25], v[216:219], v[200:203], v[22:25]
	v_mfma_f32_16x16x32_bf16 v[18:21], v[224:227], v[200:203], v[18:21]
	v_mfma_f32_16x16x32_bf16 v[6:9], v[216:219], v[208:211], v[6:9]
	v_mfma_f32_16x16x32_bf16 v[2:5], v[224:227], v[208:211], v[2:5]
	v_mfma_f32_16x16x32_bf16 v[54:57], v[220:223], v[188:191], v[54:57]
	v_mfma_f32_16x16x32_bf16 v[50:53], v[228:231], v[188:191], v[50:53]
	v_mfma_f32_16x16x32_bf16 v[38:41], v[220:223], v[196:199], v[38:41]
	v_mfma_f32_16x16x32_bf16 v[34:37], v[228:231], v[196:199], v[34:37]
	v_mfma_f32_16x16x32_bf16 v[22:25], v[220:223], v[204:207], v[22:25]
	v_mfma_f32_16x16x32_bf16 v[18:21], v[228:231], v[204:207], v[18:21]
	v_mfma_f32_16x16x32_bf16 v[6:9], v[220:223], v[212:215], v[6:9]
	v_mfma_f32_16x16x32_bf16 v[2:5], v[228:231], v[212:215], v[2:5]
	s_setprio 0
	s_add_i32 s57, s57, 2
	s_add_u32 s42, s42, 0x100
	s_addc_u32 s43, s43, 0
	s_add_u32 s55, s55, 0x100
	s_addc_u32 s56, s56, 0
	s_cmp_gt_u32 s57, 29
	s_barrier
	s_cbranch_scc0 .LBB0_1034
	v_lshl_add_u32 v150, s52, 8, v154
	v_lshl_or_b32 v134, s51, 8, v156
	v_ashrrev_i32_e32 v151, 31, v150
	v_ashrrev_i32_e32 v135, 31, v134
	v_lshlrev_b64 v[148:149], 13, v[150:151]
	v_lshl_add_u64 v[148:149], s[76:77], 0, v[148:149]
	v_lshlrev_b64 v[152:153], 2, v[134:135]
	v_lshl_add_u64 v[158:159], v[148:149], 0, v[152:153]
	v_readlane_b32 s56, v254, 30
	v_readlane_b32 s54, v254, 32
	v_readlane_b32 s60, v254, 39
	s_mov_b32 s51, s0
	s_mov_b32 s52, s22
	s_mov_b64 s[42:43], s[24:25]
	v_readlane_b32 s57, v254, 31
	v_readlane_b32 s55, v254, 33
	v_readlane_b32 s44, v254, 46
	v_readlane_b32 s61, v254, 40
	v_readlane_b32 s45, v254, 47
	v_mov_b64_e32 v[162:163], v[158:159]
	global_load_dwordx4 v[180:183], v[162:163], off
	global_load_dwordx4 v[184:187], v[162:163], off offset:16
	global_load_dwordx4 v[188:191], v[162:163], off offset:512
	global_load_dwordx4 v[192:195], v[162:163], off offset:528
	s_mov_b64 s[26:27], 0x20000
	v_lshl_add_u64 v[164:165], v[158:159], 0, s[26:27]
	global_load_dwordx4 v[196:199], v[164:165], off
	global_load_dwordx4 v[200:203], v[164:165], off offset:16
	global_load_dwordx4 v[204:207], v[164:165], off offset:512
	global_load_dwordx4 v[208:211], v[164:165], off offset:528
	s_mov_b64 s[26:27], 0x40000
	v_lshl_add_u64 v[150:151], v[158:159], 0, s[26:27]
	global_load_dwordx4 v[212:215], v[150:151], off
	global_load_dwordx4 v[216:219], v[150:151], off offset:16
	global_load_dwordx4 v[220:223], v[150:151], off offset:512
	global_load_dwordx4 v[224:227], v[150:151], off offset:528
	s_waitcnt vmcnt(8)
	v_pk_add_f32 v[126:127], v[126:127], v[180:181]
	v_pk_add_f32 v[128:129], v[128:129], v[182:183]
	v_pk_add_f32 v[122:123], v[122:123], v[184:185]
	v_pk_add_f32 v[124:125], v[124:125], v[186:187]
	v_pk_add_f32 v[118:119], v[118:119], v[188:189]
	v_pk_add_f32 v[120:121], v[120:121], v[190:191]
	v_pk_add_f32 v[114:115], v[114:115], v[192:193]
	v_pk_add_f32 v[116:117], v[116:117], v[194:195]
	global_store_dwordx4 v[162:163], v[126:129], off
	global_store_dwordx4 v[162:163], v[122:125], off offset:16
	global_store_dwordx4 v[162:163], v[118:121], off offset:512
	global_store_dwordx4 v[162:163], v[114:117], off offset:528
	s_mov_b64 s[26:27], 0x60000
	v_lshl_add_u64 v[228:229], v[158:159], 0, s[26:27]
	global_load_dwordx4 v[180:183], v[228:229], off
	global_load_dwordx4 v[184:187], v[228:229], off offset:16
	global_load_dwordx4 v[188:191], v[228:229], off offset:512
	global_load_dwordx4 v[192:195], v[228:229], off offset:528
	s_waitcnt vmcnt(12)
	v_pk_add_f32 v[110:111], v[110:111], v[196:197]
	v_pk_add_f32 v[112:113], v[112:113], v[198:199]
	v_pk_add_f32 v[106:107], v[106:107], v[200:201]
	v_pk_add_f32 v[108:109], v[108:109], v[202:203]
	v_pk_add_f32 v[102:103], v[102:103], v[204:205]
	v_pk_add_f32 v[104:105], v[104:105], v[206:207]
	v_pk_add_f32 v[98:99], v[98:99], v[208:209]
	v_pk_add_f32 v[100:101], v[100:101], v[210:211]
	global_store_dwordx4 v[164:165], v[110:113], off
	global_store_dwordx4 v[164:165], v[106:109], off offset:16
	global_store_dwordx4 v[164:165], v[102:105], off offset:512
	global_store_dwordx4 v[164:165], v[98:101], off offset:528
	s_mov_b64 s[26:27], 0x100000
	v_lshl_add_u64 v[162:163], v[158:159], 0, s[26:27]
	global_load_dwordx4 v[196:199], v[162:163], off
	global_load_dwordx4 v[200:203], v[162:163], off offset:16
	global_load_dwordx4 v[204:207], v[162:163], off offset:512
	global_load_dwordx4 v[208:211], v[162:163], off offset:528
	s_waitcnt vmcnt(16)
	v_pk_add_f32 v[94:95], v[94:95], v[212:213]
	v_pk_add_f32 v[96:97], v[96:97], v[214:215]
	v_pk_add_f32 v[90:91], v[90:91], v[216:217]
	v_pk_add_f32 v[92:93], v[92:93], v[218:219]
	v_pk_add_f32 v[86:87], v[86:87], v[220:221]
	v_pk_add_f32 v[88:89], v[88:89], v[222:223]
	v_pk_add_f32 v[82:83], v[82:83], v[224:225]
	v_pk_add_f32 v[84:85], v[84:85], v[226:227]
	global_store_dwordx4 v[150:151], v[94:97], off
	global_store_dwordx4 v[150:151], v[90:93], off offset:16
	global_store_dwordx4 v[150:151], v[86:89], off offset:512
	global_store_dwordx4 v[150:151], v[82:85], off offset:528
	s_mov_b64 s[26:27], 0x120000
	v_lshl_add_u64 v[164:165], v[158:159], 0, s[26:27]
	global_load_dwordx4 v[212:215], v[164:165], off
	global_load_dwordx4 v[216:219], v[164:165], off offset:16
	global_load_dwordx4 v[220:223], v[164:165], off offset:512
	global_load_dwordx4 v[224:227], v[164:165], off offset:528
	s_waitcnt vmcnt(16)
	v_pk_add_f32 v[78:79], v[78:79], v[180:181]
	v_pk_add_f32 v[80:81], v[80:81], v[182:183]
	v_pk_add_f32 v[74:75], v[74:75], v[184:185]
	v_pk_add_f32 v[76:77], v[76:77], v[186:187]
	v_pk_add_f32 v[70:71], v[70:71], v[188:189]
	v_pk_add_f32 v[72:73], v[72:73], v[190:191]
	v_pk_add_f32 v[66:67], v[66:67], v[192:193]
	v_pk_add_f32 v[68:69], v[68:69], v[194:195]
	global_store_dwordx4 v[228:229], v[78:81], off
	global_store_dwordx4 v[228:229], v[74:77], off offset:16
	global_store_dwordx4 v[228:229], v[70:73], off offset:512
	global_store_dwordx4 v[228:229], v[66:69], off offset:528
	s_mov_b64 s[26:27], 0x140000
	v_lshl_add_u64 v[150:151], v[158:159], 0, s[26:27]
	global_load_dwordx4 v[180:183], v[150:151], off
	global_load_dwordx4 v[184:187], v[150:151], off offset:16
	global_load_dwordx4 v[188:191], v[150:151], off offset:512
	global_load_dwordx4 v[192:195], v[150:151], off offset:528
	s_waitcnt vmcnt(16)
	v_pk_add_f32 v[62:63], v[62:63], v[196:197]
	v_pk_add_f32 v[64:65], v[64:65], v[198:199]
	v_pk_add_f32 v[58:59], v[58:59], v[200:201]
	v_pk_add_f32 v[60:61], v[60:61], v[202:203]
	v_pk_add_f32 v[54:55], v[54:55], v[204:205]
	v_pk_add_f32 v[56:57], v[56:57], v[206:207]
	v_pk_add_f32 v[50:51], v[50:51], v[208:209]
	v_pk_add_f32 v[52:53], v[52:53], v[210:211]
	global_store_dwordx4 v[162:163], v[62:65], off
	global_store_dwordx4 v[162:163], v[58:61], off offset:16
	global_store_dwordx4 v[162:163], v[54:57], off offset:512
	global_store_dwordx4 v[162:163], v[50:53], off offset:528
	s_mov_b64 s[26:27], 0x160000
	v_lshl_add_u64 v[228:229], v[158:159], 0, s[26:27]
	global_load_dwordx4 v[196:199], v[228:229], off
	global_load_dwordx4 v[200:203], v[228:229], off offset:16
	global_load_dwordx4 v[204:207], v[228:229], off offset:512
	global_load_dwordx4 v[208:211], v[228:229], off offset:528
	s_waitcnt vmcnt(16)
	v_pk_add_f32 v[46:47], v[46:47], v[212:213]
	v_pk_add_f32 v[48:49], v[48:49], v[214:215]
	v_pk_add_f32 v[42:43], v[42:43], v[216:217]
	v_pk_add_f32 v[44:45], v[44:45], v[218:219]
	v_pk_add_f32 v[38:39], v[38:39], v[220:221]
	v_pk_add_f32 v[40:41], v[40:41], v[222:223]
	v_pk_add_f32 v[34:35], v[34:35], v[224:225]
	v_pk_add_f32 v[36:37], v[36:37], v[226:227]
	global_store_dwordx4 v[164:165], v[46:49], off
	global_store_dwordx4 v[164:165], v[42:45], off offset:16
	global_store_dwordx4 v[164:165], v[38:41], off offset:512
	global_store_dwordx4 v[164:165], v[34:37], off offset:528
	s_waitcnt vmcnt(12)
	v_pk_add_f32 v[30:31], v[30:31], v[180:181]
	v_pk_add_f32 v[32:33], v[32:33], v[182:183]
	v_pk_add_f32 v[26:27], v[26:27], v[184:185]
	v_pk_add_f32 v[28:29], v[28:29], v[186:187]
	v_pk_add_f32 v[22:23], v[22:23], v[188:189]
	v_pk_add_f32 v[24:25], v[24:25], v[190:191]
	v_pk_add_f32 v[18:19], v[18:19], v[192:193]
	v_pk_add_f32 v[20:21], v[20:21], v[194:195]
	global_store_dwordx4 v[150:151], v[30:33], off
	global_store_dwordx4 v[150:151], v[26:29], off offset:16
	global_store_dwordx4 v[150:151], v[22:25], off offset:512
	global_store_dwordx4 v[150:151], v[18:21], off offset:528
	s_waitcnt vmcnt(8)
	v_pk_add_f32 v[14:15], v[14:15], v[196:197]
	v_pk_add_f32 v[16:17], v[16:17], v[198:199]
	v_pk_add_f32 v[10:11], v[10:11], v[200:201]
	v_pk_add_f32 v[12:13], v[12:13], v[202:203]
	v_pk_add_f32 v[6:7], v[6:7], v[204:205]
	v_pk_add_f32 v[8:9], v[8:9], v[206:207]
	v_pk_add_f32 v[2:3], v[2:3], v[208:209]
	v_pk_add_f32 v[4:5], v[4:5], v[210:211]
	global_store_dwordx4 v[228:229], v[14:17], off
	global_store_dwordx4 v[228:229], v[10:13], off offset:16
	global_store_dwordx4 v[228:229], v[6:9], off offset:512
	global_store_dwordx4 v[228:229], v[2:5], off offset:528
	s_mov_b32 s1, 0x160000
	s_and_b64 vcc, exec, s[38:39]
	s_mov_b64 s[26:27], s[40:41]
	s_cbranch_vccz .LBB0_1027
	s_waitcnt vmcnt(0)
	v_readlane_b32 s52, v254, 26
	v_readlane_b32 s50, v254, 28
	s_mov_b64 s[58:59], s[84:85]
	s_cmpk_gt_u32 s4, 0xff
	v_readlane_b32 s53, v254, 27
	v_readlane_b32 s51, v254, 29
	s_cbranch_scc1 .LBB0_1038
	s_barrier
